# v5 plus conv-weight L1 prefetch in delta_prep and accumulator zeroing in store order (6 GEMM instances)
# baseline (speedup 1.0000x reference)
; __device__ __forceinline__ float delta_prep(const Params& p, int l, int h, bool isP, int grow0, int t0, int nvalid, int bb, char* sm) {
;     ...
;   const int rl = tid >> 3, cg8 = tid & 7;
;   float qf[16], kf[16], vf[16];
;   {
;     const float* cw = p.conv_w + (size_t)l * 4 * 1536 + h * 128 + cg8 * 16;
; #pragma unroll
;     for (int arr = 0; arr < 3; ++arr) {
;       float y[16];
; #pragma unroll
;       for (int j = 0; j < 16; ++j) y[j] = 0.f;
;       if (rl < nvalid) {
; #pragma unroll
;       for (int j = 0; j < 4; ++j) {
;         float f[16], wv[16];
;         const bfraw* s = raw + (arr * 67 + rl + j) * 136 + cg8 * 16;
;         unpack8(*(const uint4*)s, f); unpack8(*(const uint4*)(s + 8), f + 8);
; #pragma unroll
;         for (int e = 0; e < 4; ++e) {
;           float4 t4 = *(const float4*)(cw + j * 1536 + arr * 512 + e * 4);
;           wv[e * 4] = t4.x; wv[e * 4 + 1] = t4.y; wv[e * 4 + 2] = t4.z; wv[e * 4 + 3] = t4.w;
;         }
; #pragma unroll
;         for (int e = 0; e < 16; ++e) y[e] += f[e] * wv[e];
.LBB0_913:
	s_or_b64 exec, exec, s[0:1]
	v_readlane_b32 s56, v247, 23
	s_lshl_b32 s0, s29, 2
	v_readlane_b32 s64, v247, 31
	v_lshlrev_b32_e32 v164, 4, v64
	v_readlane_b32 s65, v247, 32
	s_add_u32 s0, s64, s0
	v_and_b32_e32 v162, 0x70, v164
	v_ashrrev_i32_e32 v63, 3, v64
	s_addc_u32 s1, s65, 0
	v_lshlrev_b32_e32 v60, 2, v162
	v_lshl_add_u64 v[56:57], s[0:1], 0, v[60:61]
	s_mov_b64 s[98:99], 0x800
	global_load_dword v180, v[56:57], off
	v_lshl_add_u64 v[182:183], v[56:57], 0, s[98:99]
	global_load_dword v180, v[182:183], off
	v_lshl_add_u64 v[182:183], v[182:183], 0, s[98:99]
	global_load_dword v180, v[182:183], off
	v_lshl_add_u64 v[182:183], v[182:183], 0, s[98:99]
	global_load_dword v180, v[182:183], off
	v_lshl_add_u64 v[182:183], v[182:183], 0, s[98:99]
	global_load_dword v180, v[182:183], off
	v_lshl_add_u64 v[182:183], v[182:183], 0, s[98:99]
	global_load_dword v180, v[182:183], off
	v_lshl_add_u64 v[182:183], v[182:183], 0, s[98:99]
	global_load_dword v180, v[182:183], off
	v_lshl_add_u64 v[182:183], v[182:183], 0, s[98:99]
	global_load_dword v180, v[182:183], off
	v_lshl_add_u64 v[182:183], v[182:183], 0, s[98:99]
	global_load_dword v180, v[182:183], off
	v_lshl_add_u64 v[182:183], v[182:183], 0, s[98:99]
	global_load_dword v180, v[182:183], off
	v_lshl_add_u64 v[182:183], v[182:183], 0, s[98:99]
	global_load_dword v180, v[182:183], off
	v_lshl_add_u64 v[182:183], v[182:183], 0, s[98:99]
	global_load_dword v180, v[182:183], off
	v_cmp_gt_i32_e32 vcc, s20, v63
	v_lshl_add_u32 v58, v162, 1, s89
	v_mov_b32_e32 v66, 0
	v_mov_b32_e32 v70, 0
	v_mov_b32_e32 v71, 0
	v_mov_b32_e32 v74, 0
	v_mov_b32_e32 v75, 0
	v_mov_b32_e32 v78, 0
	v_mov_b32_e32 v79, 0
	v_mov_b32_e32 v82, 0
	v_mov_b32_e32 v83, 0
	v_mov_b32_e32 v68, 0
	v_mov_b32_e32 v69, 0
	v_mov_b32_e32 v72, 0
	v_mov_b32_e32 v73, 0
	v_mov_b32_e32 v76, 0
	v_mov_b32_e32 v77, 0
	v_mov_b32_e32 v80, 0
	v_mov_b32_e32 v81, 0
	s_waitcnt lgkmcnt(0)
	s_barrier
	v_readlane_b32 s57, v247, 24
	v_readlane_b32 s58, v247, 25
	v_readlane_b32 s59, v247, 26
	v_readlane_b32 s60, v247, 27
	v_readlane_b32 s61, v247, 28
	v_readlane_b32 s62, v247, 29
	v_readlane_b32 s63, v247, 30
	v_readlane_b32 s66, v247, 33
	v_readlane_b32 s67, v247, 34
	v_readlane_b32 s68, v247, 35
	v_readlane_b32 s69, v247, 36
	v_readlane_b32 s70, v247, 37
	v_readlane_b32 s71, v247, 38
	s_and_saveexec_b64 s[2:3], vcc
	s_cbranch_execz .LBB0_915
	v_mad_u64_u32 v[76:77], s[0:1], v63, s46, v[58:59]
	ds_read_b128 v[36:39], v76
	ds_read_b128 v[0:3], v76 offset:16
	ds_read_b128 v[40:43], v76 offset:272
	ds_read_b128 v[44:47], v76 offset:544
	ds_read_b128 v[48:51], v76 offset:816
	global_load_dwordx4 v[4:7], v[56:57], off offset:48
	global_load_dwordx4 v[12:15], v[56:57], off offset:32
	global_load_dwordx4 v[52:55], v[56:57], off offset:16
	global_load_dwordx4 v[70:73], v[56:57], off
	s_mov_b64 s[0:1], 0x1800
	s_waitcnt vmcnt(4)
	v_lshl_add_u64 v[16:17], v[56:57], 0, s[0:1]
	s_mov_b64 s[0:1], 0x3000
	s_waitcnt lgkmcnt(4)
	v_lshlrev_b32_e32 v8, 16, v36
	v_lshl_add_u64 v[20:21], v[56:57], 0, s[0:1]
	s_mov_b64 s[0:1], 0x4800
	v_and_b32_e32 v9, 0xffff0000, v36
	v_lshl_add_u64 v[68:69], v[56:57], 0, s[0:1]
	s_waitcnt lgkmcnt(2)
	v_lshlrev_b32_e32 v18, 16, v40
	v_and_b32_e32 v19, 0xffff0000, v40
	s_waitcnt lgkmcnt(1)
	v_lshlrev_b32_e32 v22, 16, v44
	v_and_b32_e32 v23, 0xffff0000, v44
	s_waitcnt lgkmcnt(0)
	v_lshlrev_b32_e32 v74, 16, v48
	v_and_b32_e32 v75, 0xffff0000, v48
	v_lshlrev_b32_e32 v40, 16, v41
	v_and_b32_e32 v41, 0xffff0000, v41
	v_lshlrev_b32_e32 v44, 16, v45
	v_and_b32_e32 v45, 0xffff0000, v45
	v_lshlrev_b32_e32 v48, 16, v49
	v_and_b32_e32 v49, 0xffff0000, v49
	s_waitcnt vmcnt(0)
	v_pk_fma_f32 v[28:29], v[70:71], v[8:9], 0 op_sel_hi:[1,1,0]
	v_add_co_u32_e64 v8, s[0:1], s76, v56
	s_nop 1
	v_addc_co_u32_e64 v9, s[0:1], 0, v57, s[0:1]
	global_load_dwordx4 v[78:81], v[8:9], off offset:2048
	s_nop 0
	global_load_dwordx4 v[8:11], v[16:17], off offset:48
	global_load_dwordx4 v[24:27], v[16:17], off offset:32
	global_load_dwordx4 v[82:85], v[16:17], off offset:16
	v_add_co_u32_e64 v16, s[0:1], s78, v56
	s_waitcnt vmcnt(3)
	v_pk_fma_f32 v[32:33], v[78:79], v[18:19], v[28:29]
	v_addc_co_u32_e64 v17, s[0:1], 0, v57, s[0:1]
	global_load_dwordx4 v[86:89], v[16:17], off
	s_nop 0
	global_load_dwordx4 v[16:19], v[20:21], off offset:48
	global_load_dwordx4 v[28:31], v[20:21], off offset:32
	global_load_dwordx4 v[90:93], v[20:21], off offset:16
	v_add_co_u32_e64 v20, s[0:1], s82, v56
	v_lshlrev_b32_e32 v78, 16, v0
	s_nop 0
	v_addc_co_u32_e64 v21, s[0:1], 0, v57, s[0:1]
	v_and_b32_e32 v79, 0xffff0000, v0
	v_pk_fma_f32 v[12:13], v[12:13], v[78:79], 0 op_sel_hi:[1,1,0]
	s_waitcnt vmcnt(3)
	v_pk_fma_f32 v[70:71], v[86:87], v[22:23], v[32:33]
	global_load_dwordx4 v[94:97], v[20:21], off offset:2048
	s_nop 0
	global_load_dwordx4 v[20:23], v[68:69], off offset:48
	global_load_dwordx4 v[32:35], v[68:69], off offset:32
	global_load_dwordx4 v[98:101], v[68:69], off offset:16
	s_waitcnt vmcnt(3)
; __device__ __forceinline__ float sigmoidf_(float x) { return __builtin_amdgcn_rcpf(1.f + __expf(-x)); }
; __device__ __forceinline__ float delta_prep(const Params& p, int l, int h, bool isP, int grow0, int t0, int nvalid, int bb, char* sm) {
;     ...
;     for (int arr = 0; arr < 3; ++arr) {
;       float y[16];
; #pragma unroll
;       for (int j = 0; j < 16; ++j) y[j] = 0.f;
;       if (rl < nvalid) {
; #pragma unroll
;       for (int j = 0; j < 4; ++j) {
;         float f[16], wv[16];
;         const bfraw* s = raw + (arr * 67 + rl + j) * 136 + cg8 * 16;
;         unpack8(*(const uint4*)s, f); unpack8(*(const uint4*)(s + 8), f + 8);
; #pragma unroll
;         for (int e = 0; e < 4; ++e) {
;           float4 t4 = *(const float4*)(cw + j * 1536 + arr * 512 + e * 4);
;           wv[e * 4] = t4.x; wv[e * 4 + 1] = t4.y; wv[e * 4 + 2] = t4.z; wv[e * 4 + 3] = t4.w;
;         }
; #pragma unroll
;         for (int e = 0; e < 16; ++e) y[e] += f[e] * wv[e];
;       }
;       float ss = 0.f;
; #pragma unroll
;       for (int e = 0; e < 16; ++e) { float v = y[e]; v = v * sigmoidf_(v); y[e] = v; ss += v * v; }
	v_pk_fma_f32 v[68:69], v[94:95], v[74:75], v[70:71]
	s_nop 0
	v_mul_f32_e32 v36, 0xbfb8aa3b, v68
	v_exp_f32_e32 v36, v36
	v_lshlrev_b32_e32 v74, 16, v50
	v_and_b32_e32 v75, 0xffff0000, v50
	v_add_f32_e32 v36, 1.0, v36
	v_rcp_f32_e32 v70, v36
	v_mul_f32_e32 v36, 0xbfb8aa3b, v69
	v_exp_f32_e32 v36, v36
	s_nop 0
	v_add_f32_e32 v36, 1.0, v36
	v_rcp_f32_e32 v71, v36
	v_lshlrev_b32_e32 v36, 16, v37
	v_and_b32_e32 v37, 0xffff0000, v37
	v_pk_fma_f32 v[36:37], v[72:73], v[36:37], 0 op_sel_hi:[1,1,0]
	v_pk_mul_f32 v[68:69], v[68:69], v[70:71]
	v_pk_fma_f32 v[36:37], v[80:81], v[40:41], v[36:37]
	v_pk_mul_f32 v[70:71], v[68:69], v[68:69]
	v_pk_fma_f32 v[36:37], v[88:89], v[44:45], v[36:37]
	v_lshlrev_b32_e32 v44, 16, v46
	v_pk_fma_f32 v[36:37], v[96:97], v[48:49], v[36:37]
	v_and_b32_e32 v45, 0xffff0000, v46
	v_mul_f32_e32 v40, 0xbfb8aa3b, v36
	v_mul_f32_e32 v41, 0xbfb8aa3b, v37
	v_exp_f32_e32 v40, v40
	v_exp_f32_e32 v41, v41
	v_add_f32_e32 v40, 1.0, v40
	v_add_f32_e32 v41, 1.0, v41
	v_rcp_f32_e32 v40, v40
	v_rcp_f32_e32 v41, v41
	s_nop 0
	v_pk_mul_f32 v[48:49], v[36:37], v[40:41]
	v_lshlrev_b32_e32 v36, 16, v38
	v_and_b32_e32 v37, 0xffff0000, v38
	v_lshlrev_b32_e32 v40, 16, v42
	v_and_b32_e32 v41, 0xffff0000, v42
	v_pk_fma_f32 v[36:37], v[52:53], v[36:37], 0 op_sel_hi:[1,1,0]
	v_lshlrev_b32_e32 v42, 16, v51
	v_pk_fma_f32 v[36:37], v[82:83], v[40:41], v[36:37]
	v_pk_mul_f32 v[72:73], v[48:49], v[48:49]
	v_pk_fma_f32 v[36:37], v[90:91], v[44:45], v[36:37]
	s_waitcnt vmcnt(0)
	v_pk_fma_f32 v[36:37], v[98:99], v[74:75], v[36:37]
	s_nop 0
	v_mul_f32_e32 v38, 0xbfb8aa3b, v36
	v_exp_f32_e32 v38, v38
	s_nop 0
	v_add_f32_e32 v38, 1.0, v38
	v_rcp_f32_e32 v40, v38
	v_mul_f32_e32 v38, 0xbfb8aa3b, v37
	v_exp_f32_e32 v38, v38
	s_nop 0
	v_add_f32_e32 v38, 1.0, v38
	v_rcp_f32_e32 v41, v38
	v_lshlrev_b32_e32 v38, 16, v43
	v_pk_mul_f32 v[52:53], v[36:37], v[40:41]
	v_lshlrev_b32_e32 v36, 16, v39
	v_and_b32_e32 v37, 0xffff0000, v39
	v_and_b32_e32 v39, 0xffff0000, v43
	v_pk_fma_f32 v[36:37], v[54:55], v[36:37], 0 op_sel_hi:[1,1,0]
	v_lshlrev_b32_e32 v40, 16, v47
	v_and_b32_e32 v41, 0xffff0000, v47
	v_pk_fma_f32 v[36:37], v[84:85], v[38:39], v[36:37]
	v_and_b32_e32 v43, 0xffff0000, v51
	v_pk_fma_f32 v[36:37], v[92:93], v[40:41], v[36:37]
	ds_read_b128 v[44:47], v76 offset:832
	v_pk_fma_f32 v[36:37], v[100:101], v[42:43], v[36:37]
	ds_read_b128 v[40:43], v76 offset:560
	v_mul_f32_e32 v38, 0xbfb8aa3b, v36
	v_mul_f32_e32 v39, 0xbfb8aa3b, v37
	v_exp_f32_e32 v38, v38
	v_exp_f32_e32 v39, v39
	s_waitcnt lgkmcnt(0)
	v_lshlrev_b32_e32 v82, 16, v40
	v_and_b32_e32 v83, 0xffff0000, v40
	v_add_f32_e32 v38, 1.0, v38
	v_add_f32_e32 v39, 1.0, v39
	v_rcp_f32_e32 v38, v38
	v_rcp_f32_e32 v39, v39
	v_and_b32_e32 v77, 0xffff0000, v44
	v_pk_mul_f32 v[74:75], v[52:53], v[52:53]
	v_pk_mul_f32 v[50:51], v[36:37], v[38:39]
	ds_read_b128 v[36:39], v76 offset:288
	v_lshlrev_b32_e32 v76, 16, v44
	v_pk_mul_f32 v[54:55], v[50:51], v[50:51]
	s_waitcnt lgkmcnt(0)
; __device__ __forceinline__ float sigmoidf_(float x) { return __builtin_amdgcn_rcpf(1.f + __expf(-x)); }
; __device__ __forceinline__ float delta_prep(const Params& p, int l, int h, bool isP, int grow0, int t0, int nvalid, int bb, char* sm) {
;     ...
;       float ss = 0.f;
; #pragma unroll
;       for (int e = 0; e < 16; ++e) { float v = y[e]; v = v * sigmoidf_(v); y[e] = v; ss += v * v; }
;       if (arr < 2) {
;         ss += __shfl_xor(ss, 1); ss += __shfl_xor(ss, 2); ss += __shfl_xor(ss, 4);
;         float sc = rsqrtf(ss + EPS) * (arr == 0 ? 0.08838834764831845f : 1.f);
; #pragma unroll
;         for (int e = 0; e < 16; ++e) y[e] *= sc;
;       }
;       }
;       const bool ok = rl < nvalid;
; #pragma unroll
;       for (int e = 0; e < 16; ++e) {
;         float v = ok ? y[e] : 0.f;
;         if (arr == 0) qf[e] = v; else if (arr == 1) kf[e] = v; else vf[e] = v;
;       }
	v_lshlrev_b32_e32 v80, 16, v36
	v_and_b32_e32 v81, 0xffff0000, v36
	v_pk_fma_f32 v[12:13], v[24:25], v[80:81], v[12:13]
	v_lshlrev_b32_e32 v36, 16, v45
	v_pk_fma_f32 v[12:13], v[28:29], v[82:83], v[12:13]
	v_lshlrev_b32_e32 v28, 16, v37
	v_pk_fma_f32 v[12:13], v[32:33], v[76:77], v[12:13]
	v_and_b32_e32 v29, 0xffff0000, v37
	v_mul_f32_e32 v0, 0xbfb8aa3b, v12
	v_exp_f32_e32 v0, v0
	v_lshlrev_b32_e32 v32, 16, v41
	v_and_b32_e32 v33, 0xffff0000, v41
	v_and_b32_e32 v37, 0xffff0000, v45
	v_add_f32_e32 v0, 1.0, v0
	v_rcp_f32_e32 v24, v0
	v_mul_f32_e32 v0, 0xbfb8aa3b, v13
	v_exp_f32_e32 v0, v0
	s_nop 0
	v_add_f32_e32 v0, 1.0, v0
	v_rcp_f32_e32 v25, v0
	v_lshlrev_b32_e32 v0, 16, v1
	v_and_b32_e32 v1, 0xffff0000, v1
	v_pk_fma_f32 v[0:1], v[14:15], v[0:1], 0 op_sel_hi:[1,1,0]
	v_pk_mul_f32 v[12:13], v[12:13], v[24:25]
	v_pk_fma_f32 v[0:1], v[26:27], v[28:29], v[0:1]
	v_lshlrev_b32_e32 v26, 16, v2
	v_and_b32_e32 v27, 0xffff0000, v2
	v_lshlrev_b32_e32 v28, 16, v38
	v_and_b32_e32 v29, 0xffff0000, v38
	v_pk_fma_f32 v[4:5], v[4:5], v[26:27], 0 op_sel_hi:[1,1,0]
	v_pk_fma_f32 v[0:1], v[30:31], v[32:33], v[0:1]
	v_lshlrev_b32_e32 v30, 16, v42
	v_and_b32_e32 v31, 0xffff0000, v42
	v_pk_fma_f32 v[4:5], v[8:9], v[28:29], v[4:5]
	v_lshlrev_b32_e32 v32, 16, v46
	v_and_b32_e32 v33, 0xffff0000, v46
	v_pk_fma_f32 v[4:5], v[16:17], v[30:31], v[4:5]
	v_pk_fma_f32 v[0:1], v[34:35], v[36:37], v[0:1]
	v_pk_fma_f32 v[4:5], v[20:21], v[32:33], v[4:5]
	v_mul_f32_e32 v14, 0xbfb8aa3b, v0
	v_mul_f32_e32 v2, 0xbfb8aa3b, v4
	v_exp_f32_e32 v2, v2
	v_mul_f32_e32 v15, 0xbfb8aa3b, v1
	v_lshlrev_b32_e32 v16, 16, v39
	v_and_b32_e32 v17, 0xffff0000, v39
	v_add_f32_e32 v2, 1.0, v2
	v_rcp_f32_e32 v8, v2
	v_mul_f32_e32 v2, 0xbfb8aa3b, v5
	v_exp_f32_e32 v2, v2
	v_exp_f32_e32 v14, v14
	v_exp_f32_e32 v15, v15
	v_lshlrev_b32_e32 v20, 16, v43
	v_add_f32_e32 v2, 1.0, v2
	v_rcp_f32_e32 v9, v2
	v_lshlrev_b32_e32 v2, 16, v3
	v_and_b32_e32 v3, 0xffff0000, v3
	v_pk_fma_f32 v[2:3], v[6:7], v[2:3], 0 op_sel_hi:[1,1,0]
	v_and_b32_e32 v21, 0xffff0000, v43
	v_pk_fma_f32 v[2:3], v[10:11], v[16:17], v[2:3]
	v_lshlrev_b32_e32 v26, 16, v47
	v_and_b32_e32 v27, 0xffff0000, v47
	v_pk_fma_f32 v[2:3], v[18:19], v[20:21], v[2:3]
	v_add_f32_e32 v10, v70, v71
	v_pk_fma_f32 v[2:3], v[22:23], v[26:27], v[2:3]
	v_add_f32_e32 v10, v10, v72
	v_mul_f32_e32 v6, 0xbfb8aa3b, v2
	v_mul_f32_e32 v7, 0xbfb8aa3b, v3
	v_add_f32_e32 v14, 1.0, v14
	v_add_f32_e32 v15, 1.0, v15
	v_exp_f32_e32 v6, v6
	v_exp_f32_e32 v7, v7
	v_add_f32_e32 v10, v10, v73
	v_rcp_f32_e32 v14, v14
	v_rcp_f32_e32 v15, v15
	v_add_f32_e32 v10, v10, v74
	v_add_f32_e32 v10, v10, v75
	v_add_f32_e32 v10, v10, v54
	v_pk_mul_f32 v[24:25], v[12:13], v[12:13]
	v_add_f32_e32 v6, 1.0, v6
	v_add_f32_e32 v7, 1.0, v7
	v_add_f32_e32 v10, v10, v55
	v_pk_mul_f32 v[0:1], v[0:1], v[14:15]
	v_rcp_f32_e32 v6, v6
	v_rcp_f32_e32 v7, v7
	v_add_f32_e32 v10, v10, v24
	v_pk_mul_f32 v[14:15], v[0:1], v[0:1]
	v_add_f32_e32 v10, v10, v25
	v_pk_mul_f32 v[4:5], v[4:5], v[8:9]
	v_add_f32_e32 v10, v10, v14
	v_pk_mul_f32 v[8:9], v[4:5], v[4:5]
	v_add_f32_e32 v10, v10, v15
	v_pk_mul_f32 v[2:3], v[2:3], v[6:7]
	v_add_f32_e32 v8, v10, v8
	v_pk_mul_f32 v[6:7], v[2:3], v[2:3]
	v_add_f32_e32 v8, v8, v9
	v_add_f32_e32 v6, v8, v6
	v_and_b32_e32 v8, 64, v158
	v_add_f32_e32 v6, v6, v7
	v_xor_b32_e32 v7, 1, v158
	v_add_u32_e32 v8, 64, v8
	v_cmp_lt_i32_e64 s[0:1], v7, v8
	s_nop 1
	v_cndmask_b32_e64 v7, v158, v7, s[0:1]
	v_lshlrev_b32_e32 v7, 2, v7
	ds_bpermute_b32 v7, v7, v6
	s_waitcnt lgkmcnt(0)
	v_add_f32_e32 v6, v6, v7
	v_xor_b32_e32 v7, 2, v158
	v_cmp_lt_i32_e64 s[0:1], v7, v8
	s_nop 1
	v_cndmask_b32_e64 v7, v158, v7, s[0:1]
	v_lshlrev_b32_e32 v7, 2, v7
	ds_bpermute_b32 v7, v7, v6
	s_waitcnt lgkmcnt(0)
	v_add_f32_e32 v6, v6, v7
	v_xor_b32_e32 v7, 4, v158
	v_cmp_lt_i32_e64 s[0:1], v7, v8
	s_nop 1
	v_cndmask_b32_e64 v7, v158, v7, s[0:1]
	v_lshlrev_b32_e32 v7, 2, v7
	ds_bpermute_b32 v7, v7, v6
	s_waitcnt lgkmcnt(0)
	v_add_f32_e32 v6, v6, v7
	v_add_f32_e32 v6, 0x358637bd, v6
	v_cmp_gt_f32_e64 s[0:1], s83, v6
	v_mul_f32_e32 v7, 0x4b800000, v6
	s_nop 0
	v_cndmask_b32_e64 v6, v6, v7, s[0:1]
	v_rsq_f32_e32 v6, v6
	s_nop 0
	v_mul_f32_e32 v7, 0x45800000, v6
	v_cndmask_b32_e64 v6, v6, v7, s[0:1]
	v_mul_f32_e32 v6, 0x3db504f3, v6
	v_pk_mul_f32 v[82:83], v[68:69], v[6:7] op_sel_hi:[1,0]
	v_pk_mul_f32 v[78:79], v[48:49], v[6:7] op_sel_hi:[1,0]
	v_pk_mul_f32 v[74:75], v[52:53], v[6:7] op_sel_hi:[1,0]
	v_pk_mul_f32 v[70:71], v[50:51], v[6:7] op_sel_hi:[1,0]
	v_pk_mul_f32 v[80:81], v[12:13], v[6:7] op_sel_hi:[1,0]
	v_pk_mul_f32 v[76:77], v[0:1], v[6:7] op_sel_hi:[1,0]
	v_pk_mul_f32 v[72:73], v[4:5], v[6:7] op_sel_hi:[1,0]
	v_pk_mul_f32 v[68:69], v[2:3], v[6:7] op_sel_hi:[1,0]

; __device__ __forceinline__ float delta_prep(const Params& p, int l, int h, bool isP, int grow0, int t0, int nvalid, int bb, char* sm) {
;     ...
;   const int rl = tid >> 3, cg8 = tid & 7;
;   float qf[16], kf[16], vf[16];
;   {
;     const float* cw = p.conv_w + (size_t)l * 4 * 1536 + h * 128 + cg8 * 16;
; #pragma unroll
;     for (int arr = 0; arr < 3; ++arr) {
;       float y[16];
; #pragma unroll
;       for (int j = 0; j < 16; ++j) y[j] = 0.f;
;       if (rl < nvalid) {
; #pragma unroll
;       for (int j = 0; j < 4; ++j) {
;         float f[16], wv[16];
;         const bfraw* s = raw + (arr * 67 + rl + j) * 136 + cg8 * 16;
;         unpack8(*(const uint4*)s, f); unpack8(*(const uint4*)(s + 8), f + 8);
; #pragma unroll
;         for (int e = 0; e < 4; ++e) {
;           float4 t4 = *(const float4*)(cw + j * 1536 + arr * 512 + e * 4);
;           wv[e * 4] = t4.x; wv[e * 4 + 1] = t4.y; wv[e * 4 + 2] = t4.z; wv[e * 4 + 3] = t4.w;
;         }
; #pragma unroll
;         for (int e = 0; e < 16; ++e) y[e] += f[e] * wv[e];
.LBB0_1344:
	s_or_b64 exec, exec, s[4:5]
	v_readlane_b32 s60, v247, 23
	s_lshl_b32 s0, s29, 2
	v_readlane_b32 s68, v247, 31
	v_lshlrev_b32_e32 v166, 4, v0
	v_readlane_b32 s69, v247, 32
	s_add_u32 s0, s68, s0
	v_and_b32_e32 v65, 0x70, v166
	v_ashrrev_i32_e32 v3, 3, v0
	s_addc_u32 s1, s69, 0
	v_lshlrev_b32_e32 v98, 2, v65
	v_mov_b32_e32 v99, v2
	v_lshl_add_u64 v[60:61], s[0:1], 0, v[98:99]
	s_mov_b64 s[98:99], 0x800
	global_load_dword v180, v[60:61], off
	v_lshl_add_u64 v[182:183], v[60:61], 0, s[98:99]
	global_load_dword v180, v[182:183], off
	v_lshl_add_u64 v[182:183], v[182:183], 0, s[98:99]
	global_load_dword v180, v[182:183], off
	v_lshl_add_u64 v[182:183], v[182:183], 0, s[98:99]
	global_load_dword v180, v[182:183], off
	v_lshl_add_u64 v[182:183], v[182:183], 0, s[98:99]
	global_load_dword v180, v[182:183], off
	v_lshl_add_u64 v[182:183], v[182:183], 0, s[98:99]
	global_load_dword v180, v[182:183], off
	v_lshl_add_u64 v[182:183], v[182:183], 0, s[98:99]
	global_load_dword v180, v[182:183], off
	v_lshl_add_u64 v[182:183], v[182:183], 0, s[98:99]
	global_load_dword v180, v[182:183], off
	v_lshl_add_u64 v[182:183], v[182:183], 0, s[98:99]
	global_load_dword v180, v[182:183], off
	v_lshl_add_u64 v[182:183], v[182:183], 0, s[98:99]
	global_load_dword v180, v[182:183], off
	v_lshl_add_u64 v[182:183], v[182:183], 0, s[98:99]
	global_load_dword v180, v[182:183], off
	v_lshl_add_u64 v[182:183], v[182:183], 0, s[98:99]
	global_load_dword v180, v[182:183], off
	v_cmp_gt_i32_e32 vcc, 8, v3
	v_lshl_add_u32 v62, v65, 1, s44
	v_mov_b32_e32 v66, 0
	v_mov_b32_e32 v70, 0
	v_mov_b32_e32 v71, 0
	v_mov_b32_e32 v74, 0
	v_mov_b32_e32 v75, 0
	v_mov_b32_e32 v78, 0
	v_mov_b32_e32 v79, 0
	v_mov_b32_e32 v82, 0
	v_mov_b32_e32 v83, 0
	v_mov_b32_e32 v68, 0
	v_mov_b32_e32 v69, 0
	v_mov_b32_e32 v72, 0
	v_mov_b32_e32 v73, 0
	v_mov_b32_e32 v76, 0
	v_mov_b32_e32 v77, 0
	v_mov_b32_e32 v80, 0
	v_mov_b32_e32 v81, 0
	s_waitcnt lgkmcnt(0)
	s_barrier
	v_readlane_b32 s61, v247, 24
	v_readlane_b32 s62, v247, 25
	v_readlane_b32 s63, v247, 26
	v_readlane_b32 s64, v247, 27
	v_readlane_b32 s65, v247, 28
	v_readlane_b32 s66, v247, 29
	v_readlane_b32 s67, v247, 30
	v_readlane_b32 s70, v247, 33
	v_readlane_b32 s71, v247, 34
	v_readlane_b32 s72, v247, 35
	v_readlane_b32 s73, v247, 36
	v_readlane_b32 s74, v247, 37
	v_readlane_b32 s75, v247, 38
	s_and_saveexec_b64 s[2:3], vcc
	s_cbranch_execz .LBB0_1346
	v_mad_u64_u32 v[76:77], s[0:1], v3, s46, v[62:63]
	ds_read_b128 v[40:43], v76
	ds_read_b128 v[4:7], v76 offset:16
	ds_read_b128 v[44:47], v76 offset:272
	ds_read_b128 v[48:51], v76 offset:544
	ds_read_b128 v[52:55], v76 offset:816
	global_load_dwordx4 v[8:11], v[60:61], off offset:48
	global_load_dwordx4 v[16:19], v[60:61], off offset:32
	global_load_dwordx4 v[56:59], v[60:61], off offset:16
	global_load_dwordx4 v[70:73], v[60:61], off
	s_mov_b64 s[0:1], 0x1800
	s_waitcnt vmcnt(4)
	v_lshl_add_u64 v[20:21], v[60:61], 0, s[0:1]
	s_mov_b64 s[0:1], 0x3000
	s_waitcnt lgkmcnt(4)
	v_lshlrev_b32_e32 v12, 16, v40
	v_lshl_add_u64 v[24:25], v[60:61], 0, s[0:1]
	s_mov_b64 s[0:1], 0x4800
	v_and_b32_e32 v13, 0xffff0000, v40
	v_lshl_add_u64 v[68:69], v[60:61], 0, s[0:1]
	s_waitcnt lgkmcnt(2)
	v_lshlrev_b32_e32 v22, 16, v44
	v_and_b32_e32 v23, 0xffff0000, v44
	s_waitcnt lgkmcnt(1)
	v_lshlrev_b32_e32 v26, 16, v48
	v_and_b32_e32 v27, 0xffff0000, v48
	s_waitcnt lgkmcnt(0)
	v_lshlrev_b32_e32 v74, 16, v52
	v_and_b32_e32 v75, 0xffff0000, v52
	v_lshlrev_b32_e32 v44, 16, v45
	v_and_b32_e32 v45, 0xffff0000, v45
	v_lshlrev_b32_e32 v48, 16, v49
	v_and_b32_e32 v49, 0xffff0000, v49
	v_lshlrev_b32_e32 v52, 16, v53
	v_and_b32_e32 v53, 0xffff0000, v53
	s_waitcnt vmcnt(0)
	v_pk_fma_f32 v[32:33], v[70:71], v[12:13], 0 op_sel_hi:[1,1,0]
	v_add_co_u32_e64 v12, s[0:1], s26, v60
	s_nop 1
	v_addc_co_u32_e64 v13, s[0:1], 0, v61, s[0:1]
	global_load_dwordx4 v[78:81], v[12:13], off offset:2048
	s_nop 0
	global_load_dwordx4 v[12:15], v[20:21], off offset:48
	global_load_dwordx4 v[28:31], v[20:21], off offset:32
	global_load_dwordx4 v[82:85], v[20:21], off offset:16
	v_add_co_u32_e64 v20, s[0:1], s27, v60
	s_waitcnt vmcnt(3)
	v_pk_fma_f32 v[36:37], v[78:79], v[22:23], v[32:33]
	v_addc_co_u32_e64 v21, s[0:1], 0, v61, s[0:1]
	global_load_dwordx4 v[86:89], v[20:21], off
	s_nop 0
	global_load_dwordx4 v[20:23], v[24:25], off offset:48
	global_load_dwordx4 v[32:35], v[24:25], off offset:32
	global_load_dwordx4 v[90:93], v[24:25], off offset:16
	v_add_co_u32_e64 v24, s[0:1], s54, v60
	v_lshlrev_b32_e32 v78, 16, v4
	s_nop 0
	v_addc_co_u32_e64 v25, s[0:1], 0, v61, s[0:1]
	v_and_b32_e32 v79, 0xffff0000, v4
	v_pk_fma_f32 v[16:17], v[16:17], v[78:79], 0 op_sel_hi:[1,1,0]
	s_waitcnt vmcnt(3)
	v_pk_fma_f32 v[70:71], v[86:87], v[26:27], v[36:37]
	global_load_dwordx4 v[94:97], v[24:25], off offset:2048
	s_nop 0
	global_load_dwordx4 v[24:27], v[68:69], off offset:48
	global_load_dwordx4 v[36:39], v[68:69], off offset:32
	global_load_dwordx4 v[100:103], v[68:69], off offset:16
	s_waitcnt vmcnt(3)
; __device__ __forceinline__ float sigmoidf_(float x) { return __builtin_amdgcn_rcpf(1.f + __expf(-x)); }
; __device__ __forceinline__ float delta_prep(const Params& p, int l, int h, bool isP, int grow0, int t0, int nvalid, int bb, char* sm) {
;     ...
;     for (int arr = 0; arr < 3; ++arr) {
;       float y[16];
; #pragma unroll
;       for (int j = 0; j < 16; ++j) y[j] = 0.f;
;       if (rl < nvalid) {
; #pragma unroll
;       for (int j = 0; j < 4; ++j) {
;         float f[16], wv[16];
;         const bfraw* s = raw + (arr * 67 + rl + j) * 136 + cg8 * 16;
;         unpack8(*(const uint4*)s, f); unpack8(*(const uint4*)(s + 8), f + 8);
; #pragma unroll
;         for (int e = 0; e < 4; ++e) {
;           float4 t4 = *(const float4*)(cw + j * 1536 + arr * 512 + e * 4);
;           wv[e * 4] = t4.x; wv[e * 4 + 1] = t4.y; wv[e * 4 + 2] = t4.z; wv[e * 4 + 3] = t4.w;
;         }
; #pragma unroll
;         for (int e = 0; e < 16; ++e) y[e] += f[e] * wv[e];
;       }
;       float ss = 0.f;
; #pragma unroll
;       for (int e = 0; e < 16; ++e) { float v = y[e]; v = v * sigmoidf_(v); y[e] = v; ss += v * v; }
	v_pk_fma_f32 v[68:69], v[94:95], v[74:75], v[70:71]
	s_nop 0
	v_mul_f32_e32 v40, 0xbfb8aa3b, v68
	v_exp_f32_e32 v40, v40
	v_lshlrev_b32_e32 v74, 16, v54
	v_and_b32_e32 v75, 0xffff0000, v54
	v_add_f32_e32 v40, 1.0, v40
	v_rcp_f32_e32 v70, v40
	v_mul_f32_e32 v40, 0xbfb8aa3b, v69
	v_exp_f32_e32 v40, v40
	s_nop 0
	v_add_f32_e32 v40, 1.0, v40
	v_rcp_f32_e32 v71, v40
	v_lshlrev_b32_e32 v40, 16, v41
	v_and_b32_e32 v41, 0xffff0000, v41
	v_pk_fma_f32 v[40:41], v[72:73], v[40:41], 0 op_sel_hi:[1,1,0]
	v_pk_mul_f32 v[68:69], v[68:69], v[70:71]
	v_pk_fma_f32 v[40:41], v[80:81], v[44:45], v[40:41]
	v_pk_mul_f32 v[70:71], v[68:69], v[68:69]
	v_pk_fma_f32 v[40:41], v[88:89], v[48:49], v[40:41]
	v_lshlrev_b32_e32 v48, 16, v50
	v_pk_fma_f32 v[40:41], v[96:97], v[52:53], v[40:41]
	v_and_b32_e32 v49, 0xffff0000, v50
	v_mul_f32_e32 v44, 0xbfb8aa3b, v40
	v_mul_f32_e32 v45, 0xbfb8aa3b, v41
	v_exp_f32_e32 v44, v44
	v_exp_f32_e32 v45, v45
	v_add_f32_e32 v44, 1.0, v44
	v_add_f32_e32 v45, 1.0, v45
	v_rcp_f32_e32 v44, v44
	v_rcp_f32_e32 v45, v45
	s_nop 0
	v_pk_mul_f32 v[52:53], v[40:41], v[44:45]
	v_lshlrev_b32_e32 v40, 16, v42
	v_and_b32_e32 v41, 0xffff0000, v42
	v_lshlrev_b32_e32 v44, 16, v46
	v_and_b32_e32 v45, 0xffff0000, v46
	v_pk_fma_f32 v[40:41], v[56:57], v[40:41], 0 op_sel_hi:[1,1,0]
	v_lshlrev_b32_e32 v46, 16, v55
	v_pk_fma_f32 v[40:41], v[82:83], v[44:45], v[40:41]
	v_pk_mul_f32 v[72:73], v[52:53], v[52:53]
	v_pk_fma_f32 v[40:41], v[90:91], v[48:49], v[40:41]
	s_waitcnt vmcnt(0)
	v_pk_fma_f32 v[40:41], v[100:101], v[74:75], v[40:41]
	s_nop 0
	v_mul_f32_e32 v42, 0xbfb8aa3b, v40
	v_exp_f32_e32 v42, v42
	s_nop 0
	v_add_f32_e32 v42, 1.0, v42
	v_rcp_f32_e32 v44, v42
	v_mul_f32_e32 v42, 0xbfb8aa3b, v41
	v_exp_f32_e32 v42, v42
	s_nop 0
	v_add_f32_e32 v42, 1.0, v42
	v_rcp_f32_e32 v45, v42
	v_lshlrev_b32_e32 v42, 16, v47
	v_pk_mul_f32 v[56:57], v[40:41], v[44:45]
	v_lshlrev_b32_e32 v40, 16, v43
	v_and_b32_e32 v41, 0xffff0000, v43
	v_and_b32_e32 v43, 0xffff0000, v47
	v_pk_fma_f32 v[40:41], v[58:59], v[40:41], 0 op_sel_hi:[1,1,0]
	v_lshlrev_b32_e32 v44, 16, v51
	v_and_b32_e32 v45, 0xffff0000, v51
	v_pk_fma_f32 v[40:41], v[84:85], v[42:43], v[40:41]
	v_and_b32_e32 v47, 0xffff0000, v55
	v_pk_fma_f32 v[40:41], v[92:93], v[44:45], v[40:41]
	ds_read_b128 v[48:51], v76 offset:832
	v_pk_fma_f32 v[40:41], v[102:103], v[46:47], v[40:41]
	ds_read_b128 v[44:47], v76 offset:560
	v_mul_f32_e32 v42, 0xbfb8aa3b, v40
	v_mul_f32_e32 v43, 0xbfb8aa3b, v41
	v_exp_f32_e32 v42, v42
	v_exp_f32_e32 v43, v43
	s_waitcnt lgkmcnt(0)
	v_lshlrev_b32_e32 v82, 16, v44
	v_and_b32_e32 v83, 0xffff0000, v44
	v_add_f32_e32 v42, 1.0, v42
	v_add_f32_e32 v43, 1.0, v43
	v_rcp_f32_e32 v42, v42
	v_rcp_f32_e32 v43, v43
	v_and_b32_e32 v77, 0xffff0000, v48
	v_pk_mul_f32 v[74:75], v[56:57], v[56:57]
	v_pk_mul_f32 v[54:55], v[40:41], v[42:43]
	ds_read_b128 v[40:43], v76 offset:288
	v_lshlrev_b32_e32 v76, 16, v48
	v_pk_mul_f32 v[58:59], v[54:55], v[54:55]
	s_waitcnt lgkmcnt(0)
; __device__ __forceinline__ float sigmoidf_(float x) { return __builtin_amdgcn_rcpf(1.f + __expf(-x)); }
; __device__ __forceinline__ float delta_prep(const Params& p, int l, int h, bool isP, int grow0, int t0, int nvalid, int bb, char* sm) {
;     ...
;       float ss = 0.f;
; #pragma unroll
;       for (int e = 0; e < 16; ++e) { float v = y[e]; v = v * sigmoidf_(v); y[e] = v; ss += v * v; }
;       if (arr < 2) {
;         ss += __shfl_xor(ss, 1); ss += __shfl_xor(ss, 2); ss += __shfl_xor(ss, 4);
;         float sc = rsqrtf(ss + EPS) * (arr == 0 ? 0.08838834764831845f : 1.f);
; #pragma unroll
;         for (int e = 0; e < 16; ++e) y[e] *= sc;
;       }
;       }
;       const bool ok = rl < nvalid;
; #pragma unroll
;       for (int e = 0; e < 16; ++e) {
;         float v = ok ? y[e] : 0.f;
;         if (arr == 0) qf[e] = v; else if (arr == 1) kf[e] = v; else vf[e] = v;
;       }
	v_lshlrev_b32_e32 v80, 16, v40
	v_and_b32_e32 v81, 0xffff0000, v40
	v_pk_fma_f32 v[16:17], v[28:29], v[80:81], v[16:17]
	v_lshlrev_b32_e32 v40, 16, v49
	v_pk_fma_f32 v[16:17], v[32:33], v[82:83], v[16:17]
	v_lshlrev_b32_e32 v32, 16, v41
	v_pk_fma_f32 v[16:17], v[36:37], v[76:77], v[16:17]
	v_and_b32_e32 v33, 0xffff0000, v41
	v_mul_f32_e32 v4, 0xbfb8aa3b, v16
	v_exp_f32_e32 v4, v4
	v_lshlrev_b32_e32 v36, 16, v45
	v_and_b32_e32 v37, 0xffff0000, v45
	v_and_b32_e32 v41, 0xffff0000, v49
	v_add_f32_e32 v4, 1.0, v4
	v_rcp_f32_e32 v28, v4
	v_mul_f32_e32 v4, 0xbfb8aa3b, v17
	v_exp_f32_e32 v4, v4
	s_nop 0
	v_add_f32_e32 v4, 1.0, v4
	v_rcp_f32_e32 v29, v4
	v_lshlrev_b32_e32 v4, 16, v5
	v_and_b32_e32 v5, 0xffff0000, v5
	v_pk_fma_f32 v[4:5], v[18:19], v[4:5], 0 op_sel_hi:[1,1,0]
	v_pk_mul_f32 v[16:17], v[16:17], v[28:29]
	v_pk_fma_f32 v[4:5], v[30:31], v[32:33], v[4:5]
	v_lshlrev_b32_e32 v30, 16, v6
	v_and_b32_e32 v31, 0xffff0000, v6
	v_lshlrev_b32_e32 v32, 16, v42
	v_and_b32_e32 v33, 0xffff0000, v42
	v_pk_fma_f32 v[8:9], v[8:9], v[30:31], 0 op_sel_hi:[1,1,0]
	v_pk_fma_f32 v[4:5], v[34:35], v[36:37], v[4:5]
	v_lshlrev_b32_e32 v34, 16, v46
	v_and_b32_e32 v35, 0xffff0000, v46
	v_pk_fma_f32 v[8:9], v[12:13], v[32:33], v[8:9]
	v_lshlrev_b32_e32 v36, 16, v50
	v_and_b32_e32 v37, 0xffff0000, v50
	v_pk_fma_f32 v[8:9], v[20:21], v[34:35], v[8:9]
	v_pk_fma_f32 v[4:5], v[38:39], v[40:41], v[4:5]
	v_pk_fma_f32 v[8:9], v[24:25], v[36:37], v[8:9]
	v_mul_f32_e32 v18, 0xbfb8aa3b, v4
	v_mul_f32_e32 v6, 0xbfb8aa3b, v8
	v_exp_f32_e32 v6, v6
	v_mul_f32_e32 v19, 0xbfb8aa3b, v5
	v_lshlrev_b32_e32 v20, 16, v43
	v_and_b32_e32 v21, 0xffff0000, v43
	v_add_f32_e32 v6, 1.0, v6
	v_rcp_f32_e32 v12, v6
	v_mul_f32_e32 v6, 0xbfb8aa3b, v9
	v_exp_f32_e32 v6, v6
	v_exp_f32_e32 v18, v18
	v_exp_f32_e32 v19, v19
	v_lshlrev_b32_e32 v24, 16, v47
	v_add_f32_e32 v6, 1.0, v6
	v_rcp_f32_e32 v13, v6
	v_lshlrev_b32_e32 v6, 16, v7
	v_and_b32_e32 v7, 0xffff0000, v7
	v_pk_fma_f32 v[6:7], v[10:11], v[6:7], 0 op_sel_hi:[1,1,0]
	v_and_b32_e32 v25, 0xffff0000, v47
	v_pk_fma_f32 v[6:7], v[14:15], v[20:21], v[6:7]
	v_lshlrev_b32_e32 v30, 16, v51
	v_and_b32_e32 v31, 0xffff0000, v51
	v_pk_fma_f32 v[6:7], v[22:23], v[24:25], v[6:7]
	v_add_f32_e32 v14, v70, v71
	v_pk_fma_f32 v[6:7], v[26:27], v[30:31], v[6:7]
	v_add_f32_e32 v14, v14, v72
	v_mul_f32_e32 v10, 0xbfb8aa3b, v6
	v_mul_f32_e32 v11, 0xbfb8aa3b, v7
	v_add_f32_e32 v18, 1.0, v18
	v_add_f32_e32 v19, 1.0, v19
	v_exp_f32_e32 v10, v10
	v_exp_f32_e32 v11, v11
	v_add_f32_e32 v14, v14, v73
	v_rcp_f32_e32 v18, v18
	v_rcp_f32_e32 v19, v19
	v_add_f32_e32 v14, v14, v74
	v_add_f32_e32 v14, v14, v75
	v_add_f32_e32 v14, v14, v58
	v_pk_mul_f32 v[28:29], v[16:17], v[16:17]
	v_add_f32_e32 v10, 1.0, v10
	v_add_f32_e32 v11, 1.0, v11
	v_add_f32_e32 v14, v14, v59
	v_pk_mul_f32 v[4:5], v[4:5], v[18:19]
	v_rcp_f32_e32 v10, v10
	v_rcp_f32_e32 v11, v11
	v_add_f32_e32 v14, v14, v28
	v_pk_mul_f32 v[18:19], v[4:5], v[4:5]
	v_add_f32_e32 v14, v14, v29
	v_pk_mul_f32 v[8:9], v[8:9], v[12:13]
	v_add_f32_e32 v14, v14, v18
	v_pk_mul_f32 v[12:13], v[8:9], v[8:9]
	v_add_f32_e32 v14, v14, v19
	v_pk_mul_f32 v[6:7], v[6:7], v[10:11]
	v_add_f32_e32 v12, v14, v12
	v_pk_mul_f32 v[10:11], v[6:7], v[6:7]
	v_add_f32_e32 v12, v12, v13
	v_add_f32_e32 v10, v12, v10
	v_and_b32_e32 v12, 64, v160
	v_add_f32_e32 v10, v10, v11
	v_xor_b32_e32 v11, 1, v160
	v_add_u32_e32 v12, 64, v12
	v_cmp_lt_i32_e64 s[0:1], v11, v12
	s_nop 1
	v_cndmask_b32_e64 v11, v160, v11, s[0:1]
	v_lshlrev_b32_e32 v11, 2, v11
	ds_bpermute_b32 v11, v11, v10
	s_waitcnt lgkmcnt(0)
	v_add_f32_e32 v10, v10, v11
	v_xor_b32_e32 v11, 2, v160
	v_cmp_lt_i32_e64 s[0:1], v11, v12
	s_nop 1
	v_cndmask_b32_e64 v11, v160, v11, s[0:1]
	v_lshlrev_b32_e32 v11, 2, v11
	ds_bpermute_b32 v11, v11, v10
	s_waitcnt lgkmcnt(0)
	v_add_f32_e32 v10, v10, v11
	v_xor_b32_e32 v11, 4, v160
	v_cmp_lt_i32_e64 s[0:1], v11, v12
	s_nop 1
	v_cndmask_b32_e64 v11, v160, v11, s[0:1]
	v_lshlrev_b32_e32 v11, 2, v11
	ds_bpermute_b32 v11, v11, v10
	s_waitcnt lgkmcnt(0)
	v_add_f32_e32 v10, v10, v11
	v_add_f32_e32 v10, 0x358637bd, v10
	v_cmp_gt_f32_e64 s[0:1], s76, v10
	v_mul_f32_e32 v11, 0x4b800000, v10
	s_nop 0
	v_cndmask_b32_e64 v10, v10, v11, s[0:1]
	v_rsq_f32_e32 v10, v10
	s_nop 0
	v_mul_f32_e32 v11, 0x45800000, v10
	v_cndmask_b32_e64 v10, v10, v11, s[0:1]
	v_mul_f32_e32 v10, 0x3db504f3, v10
	v_pk_mul_f32 v[82:83], v[68:69], v[10:11] op_sel_hi:[1,0]
	v_pk_mul_f32 v[78:79], v[52:53], v[10:11] op_sel_hi:[1,0]
	v_pk_mul_f32 v[74:75], v[56:57], v[10:11] op_sel_hi:[1,0]
	v_pk_mul_f32 v[70:71], v[54:55], v[10:11] op_sel_hi:[1,0]
	v_pk_mul_f32 v[80:81], v[16:17], v[10:11] op_sel_hi:[1,0]
	v_pk_mul_f32 v[76:77], v[4:5], v[10:11] op_sel_hi:[1,0]
	v_pk_mul_f32 v[72:73], v[8:9], v[10:11] op_sel_hi:[1,0]
	v_pk_mul_f32 v[68:69], v[6:7], v[10:11] op_sel_hi:[1,0]

; #define G8_WAIT_V(n) asm volatile("s_waitcnt vmcnt(" #n ")" ::: "memory")
; #define G8_WAIT_L(n) asm volatile("s_waitcnt lgkmcnt(" #n ")" ::: "memory")
; #define G8_BAR __builtin_amdgcn_s_barrier()
; template <class Epi, class Sched>
; __device__ __forceinline__ void gemm_phase(LAS unsigned char* lds, const Gemm g, const Sched& S, const Epi& E) {
;     ...
;     const bool has_next = S.next(ui + 1, nxt);
;     const char* nA = has_next ? (const char*)g.A + (size_t)nxt.pm * tstepA + (size_t)nxt.koff * 2 : cA; const char* nB = has_next ? (const char*)g.Bt + (size_t)nxt.pn * tstepB + (size_t)nxt.koff * 2 : cB;
;     for (int t = 0; t < nt; t += 2) {
;       const bool last = (t == nt - 2);
;       const char* a1 = cA + (size_t)(t + 1) * kstep;
;       const char* a2 = last ? nA : cA + (size_t)(t + 2) * kstep; const char* b2 = last ? nB : cB + (size_t)(t + 2) * kstep;
;       const char* a3 = a2 + kstep; const char* b3 = b2 + kstep;
;       G8_LDB(B0, 0, 0); G8_SCHED; G8_LDA(At, 0, 0); G8_STAGE(G8_SA(1, 1), a1 + hstepA, voffA);
;       G8_WAIT_L(8); G8_BAR; G8_WAIT_L(0); G8_MMA(0, 0, At, B0); G8_BAR; G8_SCHED;
;       G8_LDB(B1, 0, 1); G8_STAGE(G8_SB(0, 0), b2, voffB);
;       G8_BAR; G8_WAIT_L(0); G8_MMA(0, 1, At, B1); G8_BAR;
;       G8_LDA(At, 0, 1); G8_STAGE(G8_SA(0, 0), a2, voffA);
;       G8_BAR; G8_WAIT_L(0); G8_MMA(1, 0, At, B0); G8_BAR; G8_SCHED;
;       G8_STAGE(G8_SB(0, 1), b2 + hstepB, voffB);
;       G8_WAIT_V(6); G8_BAR; G8_MMA(1, 1, At, B1); G8_BAR;
;       G8_LDB(B0, 1, 0); G8_SCHED; G8_LDA(At, 1, 0); G8_STAGE(G8_SA(0, 1), a2 + hstepA, voffA);
;       G8_WAIT_L(8); G8_BAR; G8_WAIT_L(0); G8_MMA(0, 0, At, B0); G8_BAR; G8_SCHED;
;       G8_LDB(B1, 1, 1); G8_STAGE(G8_SB(1, 0), b3, voffB);
;       G8_BAR; G8_WAIT_L(0); G8_MMA(0, 1, At, B1); G8_BAR;
;       G8_LDA(At, 1, 1); G8_STAGE(G8_SA(1, 0), a3, voffA);
;       G8_BAR; G8_WAIT_L(0); G8_MMA(1, 0, At, B0); G8_BAR; G8_SCHED;
;       G8_STAGE(G8_SB(1, 1), b3 + hstepB, voffB);
;       G8_WAIT_V(6); G8_BAR; G8_MMA(1, 1, At, B1); G8_BAR;
;     }
;     E(acc, cur, wr, wc, fr, fq);
;     if (!has_next) break;
; #pragma unroll
;     for (int a = 0; a < 2; ++a)
; #pragma unroll
;       for (int b = 0; b < 2; ++b)
; #pragma unroll
;         for (int m = 0; m < 4; ++m)
; #pragma unroll
;           for (int n = 0; n < 2; ++n) acc[a][b][m][n] = (f32x4){0.f, 0.f, 0.f, 0.f};
;     cur = nxt; cA = nA; cB = nB; ++ui;
.LBB0_1626:
	s_ashr_i32 s15, s14, 31
	s_lshl_b64 s[28:29], s[14:15], 19
	s_add_u32 s28, s42, s28
	s_addc_u32 s29, s43, s29
	s_and_b64 s[30:31], s[40:41], exec
	s_cselect_b32 s3, s29, s37
	s_cselect_b32 s15, s28, s36
	s_ashr_i32 s17, s16, 31
	s_lshl_b64 s[30:31], s[16:17], 19
	s_add_u32 s30, s44, s30
	s_addc_u32 s31, s45, s31
	s_and_b64 s[40:41], s[40:41], exec
	s_cselect_b32 s17, s31, s39
	s_cselect_b32 s35, s30, s38
	s_add_u32 s36, s36, 0x40080
	s_addc_u32 s37, s37, 0
	s_add_u32 s59, s38, 0x100
	s_addc_u32 s60, s39, 0
	s_mov_b32 s61, -2
	v_mov_b32_e32 v127, 0
	v_mov_b32_e32 v126, 0
	v_mov_b32_e32 v125, 0
	v_mov_b32_e32 v124, 0
	v_mov_b32_e32 v123, 0
	v_mov_b32_e32 v122, 0
	v_mov_b32_e32 v121, 0
	v_mov_b32_e32 v120, 0
	v_mov_b32_e32 v119, 0
	v_mov_b32_e32 v118, 0
	v_mov_b32_e32 v117, 0
	v_mov_b32_e32 v116, 0
	v_mov_b32_e32 v115, 0
	v_mov_b32_e32 v114, 0
	v_mov_b32_e32 v113, 0
	v_mov_b32_e32 v112, 0
	v_mov_b32_e32 v111, 0
	v_mov_b32_e32 v110, 0
	v_mov_b32_e32 v109, 0
	v_mov_b32_e32 v108, 0
	v_mov_b32_e32 v107, 0
	v_mov_b32_e32 v106, 0
	v_mov_b32_e32 v105, 0
	v_mov_b32_e32 v104, 0
	v_mov_b32_e32 v103, 0
	v_mov_b32_e32 v102, 0
	v_mov_b32_e32 v101, 0
	v_mov_b32_e32 v100, 0
	v_mov_b32_e32 v99, 0
	v_mov_b32_e32 v98, 0
	v_mov_b32_e32 v97, 0
	v_mov_b32_e32 v96, 0
	v_mov_b32_e32 v95, 0
	v_mov_b32_e32 v94, 0
	v_mov_b32_e32 v93, 0
	v_mov_b32_e32 v92, 0
	v_mov_b32_e32 v91, 0
	v_mov_b32_e32 v90, 0
	v_mov_b32_e32 v89, 0
	v_mov_b32_e32 v88, 0
	v_mov_b32_e32 v87, 0
	v_mov_b32_e32 v86, 0
	v_mov_b32_e32 v85, 0
	v_mov_b32_e32 v84, 0
	v_mov_b32_e32 v83, 0
	v_mov_b32_e32 v82, 0
	v_mov_b32_e32 v81, 0
	v_mov_b32_e32 v80, 0
	v_mov_b32_e32 v79, 0
	v_mov_b32_e32 v78, 0
	v_mov_b32_e32 v77, 0
	v_mov_b32_e32 v76, 0
	v_mov_b32_e32 v75, 0
	v_mov_b32_e32 v74, 0
	v_mov_b32_e32 v73, 0
	v_mov_b32_e32 v72, 0
	v_mov_b32_e32 v71, 0
	v_mov_b32_e32 v70, 0
	v_mov_b32_e32 v69, 0
	v_mov_b32_e32 v68, 0
	v_mov_b32_e32 v67, 0
	v_mov_b32_e32 v66, 0
	v_mov_b32_e32 v65, 0
	v_mov_b32_e32 v64, 0
	v_mov_b32_e32 v63, 0
	v_mov_b32_e32 v62, 0
	v_mov_b32_e32 v61, 0
	v_mov_b32_e32 v60, 0
	v_mov_b32_e32 v59, 0
	v_mov_b32_e32 v58, 0
	v_mov_b32_e32 v57, 0
	v_mov_b32_e32 v56, 0
	v_mov_b32_e32 v55, 0
	v_mov_b32_e32 v54, 0
	v_mov_b32_e32 v53, 0
	v_mov_b32_e32 v52, 0
	v_mov_b32_e32 v51, 0
	v_mov_b32_e32 v50, 0
	v_mov_b32_e32 v49, 0
	v_mov_b32_e32 v48, 0
	v_mov_b32_e32 v47, 0
	v_mov_b32_e32 v46, 0
	v_mov_b32_e32 v45, 0
	v_mov_b32_e32 v44, 0
	v_mov_b32_e32 v43, 0
	v_mov_b32_e32 v42, 0
	v_mov_b32_e32 v41, 0
	v_mov_b32_e32 v40, 0
	v_mov_b32_e32 v39, 0
	v_mov_b32_e32 v38, 0
	v_mov_b32_e32 v37, 0
	v_mov_b32_e32 v36, 0
	v_mov_b32_e32 v35, 0
	v_mov_b32_e32 v34, 0
	v_mov_b32_e32 v33, 0
	v_mov_b32_e32 v32, 0
	v_mov_b32_e32 v31, 0
	v_mov_b32_e32 v30, 0
	v_mov_b32_e32 v29, 0
	v_mov_b32_e32 v28, 0
	v_mov_b32_e32 v27, 0
	v_mov_b32_e32 v26, 0
	v_mov_b32_e32 v25, 0
	v_mov_b32_e32 v24, 0
	v_mov_b32_e32 v23, 0
	v_mov_b32_e32 v22, 0
	v_mov_b32_e32 v21, 0
	v_mov_b32_e32 v20, 0
	v_mov_b32_e32 v19, 0
	v_mov_b32_e32 v18, 0
	v_mov_b32_e32 v17, 0
	v_mov_b32_e32 v16, 0
	v_mov_b32_e32 v15, 0
	v_mov_b32_e32 v14, 0
	v_mov_b32_e32 v13, 0
	v_mov_b32_e32 v12, 0
	v_mov_b32_e32 v11, 0
	v_mov_b32_e32 v10, 0
	v_mov_b32_e32 v9, 0
	v_mov_b32_e32 v8, 0
	v_mov_b32_e32 v7, 0
	v_mov_b32_e32 v6, 0
	v_mov_b32_e32 v5, 0
	v_mov_b32_e32 v4, 0
	v_mov_b32_e32 v3, 0
	v_mov_b32_e32 v2, 0
	v_mov_b32_e32 v1, 0
	v_mov_b32_e32 v0, 0

; #define G8_WAIT_V(n) asm volatile("s_waitcnt vmcnt(" #n ")" ::: "memory")
; #define G8_WAIT_L(n) asm volatile("s_waitcnt lgkmcnt(" #n ")" ::: "memory")
; #define G8_BAR __builtin_amdgcn_s_barrier()
; template <class Epi, class Sched>
; __device__ __forceinline__ void gemm_phase(LAS unsigned char* lds, const Gemm g, const Sched& S, const Epi& E) {
;     ...
;     const bool has_next = S.next(ui + 1, nxt);
;     const char* nA = has_next ? (const char*)g.A + (size_t)nxt.pm * tstepA + (size_t)nxt.koff * 2 : cA; const char* nB = has_next ? (const char*)g.Bt + (size_t)nxt.pn * tstepB + (size_t)nxt.koff * 2 : cB;
;     for (int t = 0; t < nt; t += 2) {
;       const bool last = (t == nt - 2);
;       const char* a1 = cA + (size_t)(t + 1) * kstep;
;       const char* a2 = last ? nA : cA + (size_t)(t + 2) * kstep; const char* b2 = last ? nB : cB + (size_t)(t + 2) * kstep;
;       const char* a3 = a2 + kstep; const char* b3 = b2 + kstep;
;       G8_LDB(B0, 0, 0); G8_SCHED; G8_LDA(At, 0, 0); G8_STAGE(G8_SA(1, 1), a1 + hstepA, voffA);
;       G8_WAIT_L(8); G8_BAR; G8_WAIT_L(0); G8_MMA(0, 0, At, B0); G8_BAR; G8_SCHED;
;       G8_LDB(B1, 0, 1); G8_STAGE(G8_SB(0, 0), b2, voffB);
;       G8_BAR; G8_WAIT_L(0); G8_MMA(0, 1, At, B1); G8_BAR;
;       G8_LDA(At, 0, 1); G8_STAGE(G8_SA(0, 0), a2, voffA);
;       G8_BAR; G8_WAIT_L(0); G8_MMA(1, 0, At, B0); G8_BAR; G8_SCHED;
;       G8_STAGE(G8_SB(0, 1), b2 + hstepB, voffB);
;       G8_WAIT_V(6); G8_BAR; G8_MMA(1, 1, At, B1); G8_BAR;
;       G8_LDB(B0, 1, 0); G8_SCHED; G8_LDA(At, 1, 0); G8_STAGE(G8_SA(0, 1), a2 + hstepA, voffA);
;       G8_WAIT_L(8); G8_BAR; G8_WAIT_L(0); G8_MMA(0, 0, At, B0); G8_BAR; G8_SCHED;
;       G8_LDB(B1, 1, 1); G8_STAGE(G8_SB(1, 0), b3, voffB);
;       G8_BAR; G8_WAIT_L(0); G8_MMA(0, 1, At, B1); G8_BAR;
;       G8_LDA(At, 1, 1); G8_STAGE(G8_SA(1, 0), a3, voffA);
;       G8_BAR; G8_WAIT_L(0); G8_MMA(1, 0, At, B0); G8_BAR; G8_SCHED;
;       G8_STAGE(G8_SB(1, 1), b3 + hstepB, voffB);
;       G8_WAIT_V(6); G8_BAR; G8_MMA(1, 1, At, B1); G8_BAR;
;     }
;     E(acc, cur, wr, wc, fr, fq);
;     if (!has_next) break;
; #pragma unroll
;     for (int a = 0; a < 2; ++a)
; #pragma unroll
;       for (int b = 0; b < 2; ++b)
; #pragma unroll
;         for (int m = 0; m < 4; ++m)
; #pragma unroll
;           for (int n = 0; n < 2; ++n) acc[a][b][m][n] = (f32x4){0.f, 0.f, 0.f, 0.f};
;     cur = nxt; cA = nA; cB = nB; ++ui;
.LBB0_1778:
	s_ashr_i32 s15, s14, 31
	s_xor_b64 s[28:29], s[40:41], -1
	s_lshl_b64 s[18:19], s[14:15], 19
	s_add_u32 s18, s33, s18
	s_addc_u32 s19, s42, s19
	s_and_b64 s[30:31], s[40:41], exec
	s_cselect_b32 s3, s19, s37
	s_cselect_b32 s15, s18, s36
	s_ashr_i32 s17, s16, 31
	s_lshl_b64 s[30:31], s[16:17], 19
	s_add_u32 s30, s43, s30
	s_addc_u32 s31, s44, s31
	s_and_b64 s[40:41], s[40:41], exec
	s_cselect_b32 s17, s31, s39
	s_cselect_b32 s35, s30, s38
	s_add_u32 s36, s36, 0x40080
	s_addc_u32 s37, s37, 0
	s_add_u32 s59, s38, 0x100
	s_addc_u32 s60, s39, 0
	s_mov_b32 s61, -2
	v_mov_b32_e32 v127, 0
	v_mov_b32_e32 v126, 0
	v_mov_b32_e32 v125, 0
	v_mov_b32_e32 v124, 0
	v_mov_b32_e32 v123, 0
	v_mov_b32_e32 v122, 0
	v_mov_b32_e32 v121, 0
	v_mov_b32_e32 v120, 0
	v_mov_b32_e32 v119, 0
	v_mov_b32_e32 v118, 0
	v_mov_b32_e32 v117, 0
	v_mov_b32_e32 v116, 0
	v_mov_b32_e32 v115, 0
	v_mov_b32_e32 v114, 0
	v_mov_b32_e32 v113, 0
	v_mov_b32_e32 v112, 0
	v_mov_b32_e32 v111, 0
	v_mov_b32_e32 v110, 0
	v_mov_b32_e32 v109, 0
	v_mov_b32_e32 v108, 0
	v_mov_b32_e32 v107, 0
	v_mov_b32_e32 v106, 0
	v_mov_b32_e32 v105, 0
	v_mov_b32_e32 v104, 0
	v_mov_b32_e32 v103, 0
	v_mov_b32_e32 v102, 0
	v_mov_b32_e32 v101, 0
	v_mov_b32_e32 v100, 0
	v_mov_b32_e32 v99, 0
	v_mov_b32_e32 v98, 0
	v_mov_b32_e32 v97, 0
	v_mov_b32_e32 v96, 0
	v_mov_b32_e32 v95, 0
	v_mov_b32_e32 v94, 0
	v_mov_b32_e32 v93, 0
	v_mov_b32_e32 v92, 0
	v_mov_b32_e32 v91, 0
	v_mov_b32_e32 v90, 0
	v_mov_b32_e32 v89, 0
	v_mov_b32_e32 v88, 0
	v_mov_b32_e32 v87, 0
	v_mov_b32_e32 v86, 0
	v_mov_b32_e32 v85, 0
	v_mov_b32_e32 v84, 0
	v_mov_b32_e32 v83, 0
	v_mov_b32_e32 v82, 0
	v_mov_b32_e32 v81, 0
	v_mov_b32_e32 v80, 0
	v_mov_b32_e32 v79, 0
	v_mov_b32_e32 v78, 0
	v_mov_b32_e32 v77, 0
	v_mov_b32_e32 v76, 0
	v_mov_b32_e32 v75, 0
	v_mov_b32_e32 v74, 0
	v_mov_b32_e32 v73, 0
	v_mov_b32_e32 v72, 0
	v_mov_b32_e32 v71, 0
	v_mov_b32_e32 v70, 0
	v_mov_b32_e32 v69, 0
	v_mov_b32_e32 v68, 0
	v_mov_b32_e32 v67, 0
	v_mov_b32_e32 v66, 0
	v_mov_b32_e32 v65, 0
	v_mov_b32_e32 v64, 0
	v_mov_b32_e32 v63, 0
	v_mov_b32_e32 v62, 0
	v_mov_b32_e32 v61, 0
	v_mov_b32_e32 v60, 0
	v_mov_b32_e32 v59, 0
	v_mov_b32_e32 v58, 0
	v_mov_b32_e32 v57, 0
	v_mov_b32_e32 v56, 0
	v_mov_b32_e32 v55, 0
	v_mov_b32_e32 v54, 0
	v_mov_b32_e32 v53, 0
	v_mov_b32_e32 v52, 0
	v_mov_b32_e32 v51, 0
	v_mov_b32_e32 v50, 0
	v_mov_b32_e32 v49, 0
	v_mov_b32_e32 v48, 0
	v_mov_b32_e32 v47, 0
	v_mov_b32_e32 v46, 0
	v_mov_b32_e32 v45, 0
	v_mov_b32_e32 v44, 0
	v_mov_b32_e32 v43, 0
	v_mov_b32_e32 v42, 0
	v_mov_b32_e32 v41, 0
	v_mov_b32_e32 v40, 0
	v_mov_b32_e32 v39, 0
	v_mov_b32_e32 v38, 0
	v_mov_b32_e32 v37, 0
	v_mov_b32_e32 v36, 0
	v_mov_b32_e32 v35, 0
	v_mov_b32_e32 v34, 0
	v_mov_b32_e32 v33, 0
	v_mov_b32_e32 v32, 0
	v_mov_b32_e32 v31, 0
	v_mov_b32_e32 v30, 0
	v_mov_b32_e32 v29, 0
	v_mov_b32_e32 v28, 0
	v_mov_b32_e32 v27, 0
	v_mov_b32_e32 v26, 0
	v_mov_b32_e32 v25, 0
	v_mov_b32_e32 v24, 0
	v_mov_b32_e32 v23, 0
	v_mov_b32_e32 v22, 0
	v_mov_b32_e32 v21, 0
	v_mov_b32_e32 v20, 0
	v_mov_b32_e32 v19, 0
	v_mov_b32_e32 v18, 0
	v_mov_b32_e32 v17, 0
	v_mov_b32_e32 v16, 0
	v_mov_b32_e32 v15, 0
	v_mov_b32_e32 v14, 0
	v_mov_b32_e32 v13, 0
	v_mov_b32_e32 v12, 0
	v_mov_b32_e32 v11, 0
	v_mov_b32_e32 v10, 0
	v_mov_b32_e32 v9, 0
	v_mov_b32_e32 v8, 0
	v_mov_b32_e32 v7, 0
	v_mov_b32_e32 v6, 0
	v_mov_b32_e32 v5, 0
	v_mov_b32_e32 v4, 0
	v_mov_b32_e32 v3, 0
	v_mov_b32_e32 v2, 0
	v_mov_b32_e32 v1, 0
	v_mov_b32_e32 v0, 0

; #define G8_WAIT_V(n) asm volatile("s_waitcnt vmcnt(" #n ")" ::: "memory")
; #define G8_WAIT_L(n) asm volatile("s_waitcnt lgkmcnt(" #n ")" ::: "memory")
; #define G8_BAR __builtin_amdgcn_s_barrier()
; template <class Epi, class Sched>
; __device__ __forceinline__ void gemm_phase(LAS unsigned char* lds, const Gemm g, const Sched& S, const Epi& E) {
;     ...
;     const bool has_next = S.next(ui + 1, nxt);
;     const char* nA = has_next ? (const char*)g.A + (size_t)nxt.pm * tstepA + (size_t)nxt.koff * 2 : cA; const char* nB = has_next ? (const char*)g.Bt + (size_t)nxt.pn * tstepB + (size_t)nxt.koff * 2 : cB;
;     for (int t = 0; t < nt; t += 2) {
;       const bool last = (t == nt - 2);
;       const char* a1 = cA + (size_t)(t + 1) * kstep;
;       const char* a2 = last ? nA : cA + (size_t)(t + 2) * kstep; const char* b2 = last ? nB : cB + (size_t)(t + 2) * kstep;
;       const char* a3 = a2 + kstep; const char* b3 = b2 + kstep;
;       G8_LDB(B0, 0, 0); G8_SCHED; G8_LDA(At, 0, 0); G8_STAGE(G8_SA(1, 1), a1 + hstepA, voffA);
;       G8_WAIT_L(8); G8_BAR; G8_WAIT_L(0); G8_MMA(0, 0, At, B0); G8_BAR; G8_SCHED;
;       G8_LDB(B1, 0, 1); G8_STAGE(G8_SB(0, 0), b2, voffB);
;       G8_BAR; G8_WAIT_L(0); G8_MMA(0, 1, At, B1); G8_BAR;
;       G8_LDA(At, 0, 1); G8_STAGE(G8_SA(0, 0), a2, voffA);
;       G8_BAR; G8_WAIT_L(0); G8_MMA(1, 0, At, B0); G8_BAR; G8_SCHED;
;       G8_STAGE(G8_SB(0, 1), b2 + hstepB, voffB);
;       G8_WAIT_V(6); G8_BAR; G8_MMA(1, 1, At, B1); G8_BAR;
;       G8_LDB(B0, 1, 0); G8_SCHED; G8_LDA(At, 1, 0); G8_STAGE(G8_SA(0, 1), a2 + hstepA, voffA);
;       G8_WAIT_L(8); G8_BAR; G8_WAIT_L(0); G8_MMA(0, 0, At, B0); G8_BAR; G8_SCHED;
;       G8_LDB(B1, 1, 1); G8_STAGE(G8_SB(1, 0), b3, voffB);
;       G8_BAR; G8_WAIT_L(0); G8_MMA(0, 1, At, B1); G8_BAR;
;       G8_LDA(At, 1, 1); G8_STAGE(G8_SA(1, 0), a3, voffA);
;       G8_BAR; G8_WAIT_L(0); G8_MMA(1, 0, At, B0); G8_BAR; G8_SCHED;
;       G8_STAGE(G8_SB(1, 1), b3 + hstepB, voffB);
;       G8_WAIT_V(6); G8_BAR; G8_MMA(1, 1, At, B1); G8_BAR;
;     }
;     E(acc, cur, wr, wc, fr, fq);
;     if (!has_next) break;
; #pragma unroll
;     for (int a = 0; a < 2; ++a)
; #pragma unroll
;       for (int b = 0; b < 2; ++b)
; #pragma unroll
;         for (int m = 0; m < 4; ++m)
; #pragma unroll
;           for (int n = 0; n < 2; ++n) acc[a][b][m][n] = (f32x4){0.f, 0.f, 0.f, 0.f};
;     cur = nxt; cA = nA; cB = nB; ++ui;
.LBB0_1936:
	s_ashr_i32 s11, s10, 31
	v_cmp_lt_i64_e32 vcc, s[12:13], v[204:205]
	s_lshl_b64 s[12:13], s[10:11], 20
	s_add_u32 s12, s33, s12
	s_addc_u32 s13, s34, s13
	s_and_b64 s[14:15], vcc, exec
	s_cselect_b32 s11, s13, s19
	s_cselect_b32 s55, s12, s18
	s_ashr_i32 s9, s8, 31
	s_lshl_b64 s[14:15], s[8:9], 18
	s_add_u32 s14, s35, s14
	s_addc_u32 s15, s36, s15
	s_and_b64 s[30:31], vcc, exec
	s_cselect_b32 s9, s15, s29
	s_cselect_b32 s56, s14, s28
	s_add_u32 s18, s18, 0x80080
	s_addc_u32 s19, s19, 0
	s_add_u32 s57, s28, 0x100
	s_addc_u32 s58, s29, 0
	s_mov_b32 s59, -2
	v_mov_b32_e32 v127, 0
	v_mov_b32_e32 v126, 0
	v_mov_b32_e32 v125, 0
	v_mov_b32_e32 v124, 0
	v_mov_b32_e32 v123, 0
	v_mov_b32_e32 v122, 0
	v_mov_b32_e32 v121, 0
	v_mov_b32_e32 v120, 0
	v_mov_b32_e32 v119, 0
	v_mov_b32_e32 v118, 0
	v_mov_b32_e32 v117, 0
	v_mov_b32_e32 v116, 0
	v_mov_b32_e32 v115, 0
	v_mov_b32_e32 v114, 0
	v_mov_b32_e32 v113, 0
	v_mov_b32_e32 v112, 0
	v_mov_b32_e32 v111, 0
	v_mov_b32_e32 v110, 0
	v_mov_b32_e32 v109, 0
	v_mov_b32_e32 v108, 0
	v_mov_b32_e32 v107, 0
	v_mov_b32_e32 v106, 0
	v_mov_b32_e32 v105, 0
	v_mov_b32_e32 v104, 0
	v_mov_b32_e32 v103, 0
	v_mov_b32_e32 v102, 0
	v_mov_b32_e32 v101, 0
	v_mov_b32_e32 v100, 0
	v_mov_b32_e32 v99, 0
	v_mov_b32_e32 v98, 0
	v_mov_b32_e32 v97, 0
	v_mov_b32_e32 v96, 0
	v_mov_b32_e32 v95, 0
	v_mov_b32_e32 v94, 0
	v_mov_b32_e32 v93, 0
	v_mov_b32_e32 v92, 0
	v_mov_b32_e32 v91, 0
	v_mov_b32_e32 v90, 0
	v_mov_b32_e32 v89, 0
	v_mov_b32_e32 v88, 0
	v_mov_b32_e32 v87, 0
	v_mov_b32_e32 v86, 0
	v_mov_b32_e32 v85, 0
	v_mov_b32_e32 v84, 0
	v_mov_b32_e32 v83, 0
	v_mov_b32_e32 v82, 0
	v_mov_b32_e32 v81, 0
	v_mov_b32_e32 v80, 0
	v_mov_b32_e32 v79, 0
	v_mov_b32_e32 v78, 0
	v_mov_b32_e32 v77, 0
	v_mov_b32_e32 v76, 0
	v_mov_b32_e32 v75, 0
	v_mov_b32_e32 v74, 0
	v_mov_b32_e32 v73, 0
	v_mov_b32_e32 v72, 0
	v_mov_b32_e32 v71, 0
	v_mov_b32_e32 v70, 0
	v_mov_b32_e32 v69, 0
	v_mov_b32_e32 v68, 0
	v_mov_b32_e32 v67, 0
	v_mov_b32_e32 v66, 0
	v_mov_b32_e32 v65, 0
	v_mov_b32_e32 v64, 0
	v_mov_b32_e32 v63, 0
	v_mov_b32_e32 v62, 0
	v_mov_b32_e32 v61, 0
	v_mov_b32_e32 v60, 0
	v_mov_b32_e32 v59, 0
	v_mov_b32_e32 v58, 0
	v_mov_b32_e32 v57, 0
	v_mov_b32_e32 v56, 0
	v_mov_b32_e32 v55, 0
	v_mov_b32_e32 v54, 0
	v_mov_b32_e32 v53, 0
	v_mov_b32_e32 v52, 0
	v_mov_b32_e32 v51, 0
	v_mov_b32_e32 v50, 0
	v_mov_b32_e32 v49, 0
	v_mov_b32_e32 v48, 0
	v_mov_b32_e32 v47, 0
	v_mov_b32_e32 v46, 0
	v_mov_b32_e32 v45, 0
	v_mov_b32_e32 v44, 0
	v_mov_b32_e32 v43, 0
	v_mov_b32_e32 v42, 0
	v_mov_b32_e32 v41, 0
	v_mov_b32_e32 v40, 0
	v_mov_b32_e32 v39, 0
	v_mov_b32_e32 v38, 0
	v_mov_b32_e32 v37, 0
	v_mov_b32_e32 v36, 0
	v_mov_b32_e32 v35, 0
	v_mov_b32_e32 v34, 0
	v_mov_b32_e32 v33, 0
	v_mov_b32_e32 v32, 0
	v_mov_b32_e32 v31, 0
	v_mov_b32_e32 v30, 0
	v_mov_b32_e32 v29, 0
	v_mov_b32_e32 v28, 0
	v_mov_b32_e32 v27, 0
	v_mov_b32_e32 v26, 0
	v_mov_b32_e32 v25, 0
	v_mov_b32_e32 v24, 0
	v_mov_b32_e32 v23, 0
	v_mov_b32_e32 v22, 0
	v_mov_b32_e32 v21, 0
	v_mov_b32_e32 v20, 0
	v_mov_b32_e32 v19, 0
	v_mov_b32_e32 v18, 0
	v_mov_b32_e32 v17, 0
	v_mov_b32_e32 v16, 0
	v_mov_b32_e32 v15, 0
	v_mov_b32_e32 v14, 0
	v_mov_b32_e32 v13, 0
	v_mov_b32_e32 v12, 0
	v_mov_b32_e32 v11, 0
	v_mov_b32_e32 v10, 0
	v_mov_b32_e32 v9, 0
	v_mov_b32_e32 v8, 0
	v_mov_b32_e32 v7, 0
	v_mov_b32_e32 v6, 0
	v_mov_b32_e32 v5, 0
	v_mov_b32_e32 v4, 0
	v_mov_b32_e32 v3, 0
	v_mov_b32_e32 v2, 0
	v_mov_b32_e32 v1, 0
	v_mov_b32_e32 v0, 0

; #define G8_WAIT_V(n) asm volatile("s_waitcnt vmcnt(" #n ")" ::: "memory")
; #define G8_WAIT_L(n) asm volatile("s_waitcnt lgkmcnt(" #n ")" ::: "memory")
; #define G8_BAR __builtin_amdgcn_s_barrier()
; template <class Epi, class Sched>
; __device__ __forceinline__ void gemm_phase(LAS unsigned char* lds, const Gemm g, const Sched& S, const Epi& E) {
;     ...
;     const bool has_next = S.next(ui + 1, nxt);
;     const char* nA = has_next ? (const char*)g.A + (size_t)nxt.pm * tstepA + (size_t)nxt.koff * 2 : cA; const char* nB = has_next ? (const char*)g.Bt + (size_t)nxt.pn * tstepB + (size_t)nxt.koff * 2 : cB;
;     for (int t = 0; t < nt; t += 2) {
;       const bool last = (t == nt - 2);
;       const char* a1 = cA + (size_t)(t + 1) * kstep;
;       const char* a2 = last ? nA : cA + (size_t)(t + 2) * kstep; const char* b2 = last ? nB : cB + (size_t)(t + 2) * kstep;
;       const char* a3 = a2 + kstep; const char* b3 = b2 + kstep;
;       G8_LDB(B0, 0, 0); G8_SCHED; G8_LDA(At, 0, 0); G8_STAGE(G8_SA(1, 1), a1 + hstepA, voffA);
;       G8_WAIT_L(8); G8_BAR; G8_WAIT_L(0); G8_MMA(0, 0, At, B0); G8_BAR; G8_SCHED;
;       G8_LDB(B1, 0, 1); G8_STAGE(G8_SB(0, 0), b2, voffB);
;       G8_BAR; G8_WAIT_L(0); G8_MMA(0, 1, At, B1); G8_BAR;
;       G8_LDA(At, 0, 1); G8_STAGE(G8_SA(0, 0), a2, voffA);
;       G8_BAR; G8_WAIT_L(0); G8_MMA(1, 0, At, B0); G8_BAR; G8_SCHED;
;       G8_STAGE(G8_SB(0, 1), b2 + hstepB, voffB);
;       G8_WAIT_V(6); G8_BAR; G8_MMA(1, 1, At, B1); G8_BAR;
;       G8_LDB(B0, 1, 0); G8_SCHED; G8_LDA(At, 1, 0); G8_STAGE(G8_SA(0, 1), a2 + hstepA, voffA);
;       G8_WAIT_L(8); G8_BAR; G8_WAIT_L(0); G8_MMA(0, 0, At, B0); G8_BAR; G8_SCHED;
;       G8_LDB(B1, 1, 1); G8_STAGE(G8_SB(1, 0), b3, voffB);
;       G8_BAR; G8_WAIT_L(0); G8_MMA(0, 1, At, B1); G8_BAR;
;       G8_LDA(At, 1, 1); G8_STAGE(G8_SA(1, 0), a3, voffA);
;       G8_BAR; G8_WAIT_L(0); G8_MMA(1, 0, At, B0); G8_BAR; G8_SCHED;
;       G8_STAGE(G8_SB(1, 1), b3 + hstepB, voffB);
;       G8_WAIT_V(6); G8_BAR; G8_MMA(1, 1, At, B1); G8_BAR;
;     }
;     E(acc, cur, wr, wc, fr, fq);
;     if (!has_next) break;
; #pragma unroll
;     for (int a = 0; a < 2; ++a)
; #pragma unroll
;       for (int b = 0; b < 2; ++b)
; #pragma unroll
;         for (int m = 0; m < 4; ++m)
; #pragma unroll
;           for (int n = 0; n < 2; ++n) acc[a][b][m][n] = (f32x4){0.f, 0.f, 0.f, 0.f};
;     cur = nxt; cA = nA; cB = nB; ++ui;
.LBB0_1958:
	s_ashr_i32 s11, s10, 31
	s_lshl_b64 s[14:15], s[10:11], 18
	s_add_u32 s14, s33, s14
	s_addc_u32 s15, s34, s15
	s_and_b64 s[4:5], s[4:5], exec
	s_cselect_b32 s11, s15, s19
	s_cselect_b32 s50, s14, s18
	s_add_u32 s51, s18, 0x100
	s_addc_u32 s52, s19, 0
	s_mov_b32 s53, -2
	v_mov_b32_e32 v127, 0
	v_mov_b32_e32 v126, 0
	v_mov_b32_e32 v125, 0
	v_mov_b32_e32 v124, 0
	v_mov_b32_e32 v123, 0
	v_mov_b32_e32 v122, 0
	v_mov_b32_e32 v121, 0
	v_mov_b32_e32 v120, 0
	v_mov_b32_e32 v119, 0
	v_mov_b32_e32 v118, 0
	v_mov_b32_e32 v117, 0
	v_mov_b32_e32 v116, 0
	v_mov_b32_e32 v115, 0
	v_mov_b32_e32 v114, 0
	v_mov_b32_e32 v113, 0
	v_mov_b32_e32 v112, 0
	v_mov_b32_e32 v111, 0
	v_mov_b32_e32 v110, 0
	v_mov_b32_e32 v109, 0
	v_mov_b32_e32 v108, 0
	v_mov_b32_e32 v107, 0
	v_mov_b32_e32 v106, 0
	v_mov_b32_e32 v105, 0
	v_mov_b32_e32 v104, 0
	v_mov_b32_e32 v103, 0
	v_mov_b32_e32 v102, 0
	v_mov_b32_e32 v101, 0
	v_mov_b32_e32 v100, 0
	v_mov_b32_e32 v99, 0
	v_mov_b32_e32 v98, 0
	v_mov_b32_e32 v97, 0
	v_mov_b32_e32 v96, 0
	v_mov_b32_e32 v95, 0
	v_mov_b32_e32 v94, 0
	v_mov_b32_e32 v93, 0
	v_mov_b32_e32 v92, 0
	v_mov_b32_e32 v91, 0
	v_mov_b32_e32 v90, 0
	v_mov_b32_e32 v89, 0
	v_mov_b32_e32 v88, 0
	v_mov_b32_e32 v87, 0
	v_mov_b32_e32 v86, 0
	v_mov_b32_e32 v85, 0
	v_mov_b32_e32 v84, 0
	v_mov_b32_e32 v83, 0
	v_mov_b32_e32 v82, 0
	v_mov_b32_e32 v81, 0
	v_mov_b32_e32 v80, 0
	v_mov_b32_e32 v79, 0
	v_mov_b32_e32 v78, 0
	v_mov_b32_e32 v77, 0
	v_mov_b32_e32 v76, 0
	v_mov_b32_e32 v75, 0
	v_mov_b32_e32 v74, 0
	v_mov_b32_e32 v73, 0
	v_mov_b32_e32 v72, 0
	v_mov_b32_e32 v71, 0
	v_mov_b32_e32 v70, 0
	v_mov_b32_e32 v69, 0
	v_mov_b32_e32 v68, 0
	v_mov_b32_e32 v67, 0
	v_mov_b32_e32 v66, 0
	v_mov_b32_e32 v65, 0
	v_mov_b32_e32 v64, 0
	v_mov_b32_e32 v63, 0
	v_mov_b32_e32 v62, 0
	v_mov_b32_e32 v61, 0
	v_mov_b32_e32 v60, 0
	v_mov_b32_e32 v59, 0
	v_mov_b32_e32 v58, 0
	v_mov_b32_e32 v57, 0
	v_mov_b32_e32 v56, 0
	v_mov_b32_e32 v55, 0
	v_mov_b32_e32 v54, 0
	v_mov_b32_e32 v53, 0
	v_mov_b32_e32 v52, 0
	v_mov_b32_e32 v51, 0
	v_mov_b32_e32 v50, 0
	v_mov_b32_e32 v49, 0
	v_mov_b32_e32 v48, 0
	v_mov_b32_e32 v47, 0
	v_mov_b32_e32 v46, 0
	v_mov_b32_e32 v45, 0
	v_mov_b32_e32 v44, 0
	v_mov_b32_e32 v43, 0
	v_mov_b32_e32 v42, 0
	v_mov_b32_e32 v41, 0
	v_mov_b32_e32 v40, 0
	v_mov_b32_e32 v39, 0
	v_mov_b32_e32 v38, 0
	v_mov_b32_e32 v37, 0
	v_mov_b32_e32 v36, 0
	v_mov_b32_e32 v35, 0
	v_mov_b32_e32 v34, 0
	v_mov_b32_e32 v33, 0
	v_mov_b32_e32 v32, 0
	v_mov_b32_e32 v31, 0
	v_mov_b32_e32 v30, 0
	v_mov_b32_e32 v29, 0
	v_mov_b32_e32 v28, 0
	v_mov_b32_e32 v27, 0
	v_mov_b32_e32 v26, 0
	v_mov_b32_e32 v25, 0
	v_mov_b32_e32 v24, 0
	v_mov_b32_e32 v23, 0
	v_mov_b32_e32 v22, 0
	v_mov_b32_e32 v21, 0
	v_mov_b32_e32 v20, 0
	v_mov_b32_e32 v19, 0
	v_mov_b32_e32 v18, 0
	v_mov_b32_e32 v17, 0
	v_mov_b32_e32 v16, 0
	v_mov_b32_e32 v15, 0
	v_mov_b32_e32 v14, 0
	v_mov_b32_e32 v13, 0
	v_mov_b32_e32 v12, 0
	v_mov_b32_e32 v11, 0
	v_mov_b32_e32 v10, 0
	v_mov_b32_e32 v9, 0
	v_mov_b32_e32 v8, 0
	v_mov_b32_e32 v7, 0
	v_mov_b32_e32 v6, 0
	v_mov_b32_e32 v5, 0
	v_mov_b32_e32 v4, 0
	v_mov_b32_e32 v3, 0
	v_mov_b32_e32 v2, 0
	v_mov_b32_e32 v1, 0
	v_mov_b32_e32 v0, 0

; __device__ __forceinline__ float sigmoidf_(float x) { return __builtin_amdgcn_rcpf(1.f + __expf(-x)); }
; __device__ __forceinline__ float delta_prep(const Params& p, int l, int h, bool isP, int grow0, int t0, int nvalid, int bb, char* sm) {
;     ...
;   __syncthreads();
;   const int rl = tid >> 3, cg8 = tid & 7;
;   float qf[16], kf[16], vf[16];
;   {
;     const float* cw = p.conv_w + (size_t)l * 4 * 1536 + h * 128 + cg8 * 16;
; #pragma unroll
;     for (int arr = 0; arr < 3; ++arr) {
;       float y[16];
; #pragma unroll
;       for (int j = 0; j < 16; ++j) y[j] = 0.f;
;       if (rl < nvalid) {
; #pragma unroll
;       for (int j = 0; j < 4; ++j) {
;         float f[16], wv[16];
;         const bfraw* s = raw + (arr * 67 + rl + j) * 136 + cg8 * 16;
;         unpack8(*(const uint4*)s, f); unpack8(*(const uint4*)(s + 8), f + 8);
; #pragma unroll
;         for (int e = 0; e < 4; ++e) {
;           float4 t4 = *(const float4*)(cw + j * 1536 + arr * 512 + e * 4);
;           wv[e * 4] = t4.x; wv[e * 4 + 1] = t4.y; wv[e * 4 + 2] = t4.z; wv[e * 4 + 3] = t4.w;
;         }
; #pragma unroll
;         for (int e = 0; e < 16; ++e) y[e] += f[e] * wv[e];
;       }
;       float ss = 0.f;
; #pragma unroll
;       for (int e = 0; e < 16; ++e) { float v = y[e]; v = v * sigmoidf_(v); y[e] = v; ss += v * v; }
.LBB0_3671:
	s_or_b64 exec, exec, s[18:19]
	s_lshl_b32 s0, s30, 2
	v_lshlrev_b32_e32 v164, 4, v64
	s_add_u32 s0, s46, s0
	v_and_b32_e32 v162, 0x70, v164
	v_ashrrev_i32_e32 v63, 3, v64
	s_addc_u32 s1, s47, 0
	v_lshlrev_b32_e32 v60, 2, v162
	v_lshl_add_u64 v[56:57], s[0:1], 0, v[60:61]
	s_mov_b64 s[98:99], 0x800
	global_load_dword v180, v[56:57], off
	v_lshl_add_u64 v[182:183], v[56:57], 0, s[98:99]
	global_load_dword v180, v[182:183], off
	v_lshl_add_u64 v[182:183], v[182:183], 0, s[98:99]
	global_load_dword v180, v[182:183], off
	v_lshl_add_u64 v[182:183], v[182:183], 0, s[98:99]
	global_load_dword v180, v[182:183], off
	v_lshl_add_u64 v[182:183], v[182:183], 0, s[98:99]
	global_load_dword v180, v[182:183], off
	v_lshl_add_u64 v[182:183], v[182:183], 0, s[98:99]
	global_load_dword v180, v[182:183], off
	v_lshl_add_u64 v[182:183], v[182:183], 0, s[98:99]
	global_load_dword v180, v[182:183], off
	v_lshl_add_u64 v[182:183], v[182:183], 0, s[98:99]
	global_load_dword v180, v[182:183], off
	v_lshl_add_u64 v[182:183], v[182:183], 0, s[98:99]
	global_load_dword v180, v[182:183], off
	v_lshl_add_u64 v[182:183], v[182:183], 0, s[98:99]
	global_load_dword v180, v[182:183], off
	v_lshl_add_u64 v[182:183], v[182:183], 0, s[98:99]
	global_load_dword v180, v[182:183], off
	v_lshl_add_u64 v[182:183], v[182:183], 0, s[98:99]
	global_load_dword v180, v[182:183], off
	v_cmp_gt_i32_e32 vcc, s29, v63
	v_lshl_add_u32 v58, v162, 1, s88
	v_mov_b32_e32 v66, 0
	v_mov_b32_e32 v70, 0
	v_mov_b32_e32 v71, 0
	v_mov_b32_e32 v74, 0
	v_mov_b32_e32 v75, 0
	v_mov_b32_e32 v78, 0
	v_mov_b32_e32 v79, 0
	v_mov_b32_e32 v82, 0
	v_mov_b32_e32 v83, 0
	v_mov_b32_e32 v68, 0
	v_mov_b32_e32 v69, 0
	v_mov_b32_e32 v72, 0
	v_mov_b32_e32 v73, 0
	v_mov_b32_e32 v76, 0
	v_mov_b32_e32 v77, 0
	v_mov_b32_e32 v80, 0
	v_mov_b32_e32 v81, 0
	s_waitcnt lgkmcnt(0)
	s_barrier
	s_and_saveexec_b64 s[2:3], vcc
	s_cbranch_execz .LBB0_3673
	v_mad_u64_u32 v[76:77], s[0:1], v63, s57, v[58:59]
	ds_read_b128 v[36:39], v76
	ds_read_b128 v[0:3], v76 offset:16
	ds_read_b128 v[40:43], v76 offset:272
	ds_read_b128 v[44:47], v76 offset:544
	ds_read_b128 v[48:51], v76 offset:816
	global_load_dwordx4 v[4:7], v[56:57], off offset:48
	global_load_dwordx4 v[12:15], v[56:57], off offset:32
	global_load_dwordx4 v[52:55], v[56:57], off offset:16
	global_load_dwordx4 v[70:73], v[56:57], off
	s_mov_b64 s[0:1], 0x1800
	s_waitcnt vmcnt(4)
	v_lshl_add_u64 v[16:17], v[56:57], 0, s[0:1]
	s_mov_b64 s[0:1], 0x3000
	s_waitcnt lgkmcnt(4)
	v_lshlrev_b32_e32 v8, 16, v36
	v_lshl_add_u64 v[20:21], v[56:57], 0, s[0:1]
	s_mov_b64 s[0:1], 0x4800
	v_and_b32_e32 v9, 0xffff0000, v36
	v_lshl_add_u64 v[68:69], v[56:57], 0, s[0:1]
	s_waitcnt lgkmcnt(2)
	v_lshlrev_b32_e32 v18, 16, v40
	v_and_b32_e32 v19, 0xffff0000, v40
	s_waitcnt lgkmcnt(1)
	v_lshlrev_b32_e32 v22, 16, v44
	v_and_b32_e32 v23, 0xffff0000, v44
	s_waitcnt lgkmcnt(0)
	v_lshlrev_b32_e32 v74, 16, v48
	v_and_b32_e32 v75, 0xffff0000, v48
	v_lshlrev_b32_e32 v40, 16, v41
	v_and_b32_e32 v41, 0xffff0000, v41
	v_lshlrev_b32_e32 v44, 16, v45
	v_and_b32_e32 v45, 0xffff0000, v45
	v_lshlrev_b32_e32 v48, 16, v49
	v_and_b32_e32 v49, 0xffff0000, v49
	s_waitcnt vmcnt(0)
	v_pk_fma_f32 v[28:29], v[70:71], v[8:9], 0 op_sel_hi:[1,1,0]
	v_add_co_u32_e64 v8, s[0:1], s72, v56
	s_nop 1
	v_addc_co_u32_e64 v9, s[0:1], 0, v57, s[0:1]
	global_load_dwordx4 v[78:81], v[8:9], off offset:2048
	s_nop 0
	global_load_dwordx4 v[8:11], v[16:17], off offset:48
	global_load_dwordx4 v[24:27], v[16:17], off offset:32
	global_load_dwordx4 v[82:85], v[16:17], off offset:16
	v_add_co_u32_e64 v16, s[0:1], s74, v56
	s_waitcnt vmcnt(3)
	v_pk_fma_f32 v[32:33], v[78:79], v[18:19], v[28:29]
	v_addc_co_u32_e64 v17, s[0:1], 0, v57, s[0:1]
	global_load_dwordx4 v[86:89], v[16:17], off
	s_nop 0
	global_load_dwordx4 v[16:19], v[20:21], off offset:48
	global_load_dwordx4 v[28:31], v[20:21], off offset:32
	global_load_dwordx4 v[90:93], v[20:21], off offset:16
	v_add_co_u32_e64 v20, s[0:1], s76, v56
	v_lshlrev_b32_e32 v78, 16, v0
	s_nop 0
	v_addc_co_u32_e64 v21, s[0:1], 0, v57, s[0:1]
	v_and_b32_e32 v79, 0xffff0000, v0
	v_pk_fma_f32 v[12:13], v[12:13], v[78:79], 0 op_sel_hi:[1,1,0]
	s_waitcnt vmcnt(3)
	v_pk_fma_f32 v[70:71], v[86:87], v[22:23], v[32:33]
	global_load_dwordx4 v[94:97], v[20:21], off offset:2048
	s_nop 0
	global_load_dwordx4 v[20:23], v[68:69], off offset:48
	global_load_dwordx4 v[32:35], v[68:69], off offset:32
	global_load_dwordx4 v[98:101], v[68:69], off offset:16
	s_waitcnt vmcnt(3)
	v_pk_fma_f32 v[68:69], v[94:95], v[74:75], v[70:71]
	s_nop 0
	v_mul_f32_e32 v36, 0xbfb8aa3b, v68
	v_exp_f32_e32 v36, v36
	v_lshlrev_b32_e32 v74, 16, v50
	v_and_b32_e32 v75, 0xffff0000, v50
	v_add_f32_e32 v36, 1.0, v36
	v_rcp_f32_e32 v70, v36
	v_mul_f32_e32 v36, 0xbfb8aa3b, v69
	v_exp_f32_e32 v36, v36
	s_nop 0
	v_add_f32_e32 v36, 1.0, v36
	v_rcp_f32_e32 v71, v36
	v_lshlrev_b32_e32 v36, 16, v37
	v_and_b32_e32 v37, 0xffff0000, v37
	v_pk_fma_f32 v[36:37], v[72:73], v[36:37], 0 op_sel_hi:[1,1,0]
	v_pk_mul_f32 v[68:69], v[68:69], v[70:71]
	v_pk_fma_f32 v[36:37], v[80:81], v[40:41], v[36:37]
	v_pk_mul_f32 v[70:71], v[68:69], v[68:69]
	v_pk_fma_f32 v[36:37], v[88:89], v[44:45], v[36:37]
	v_lshlrev_b32_e32 v44, 16, v46
	v_pk_fma_f32 v[36:37], v[96:97], v[48:49], v[36:37]
	v_and_b32_e32 v45, 0xffff0000, v46
	v_mul_f32_e32 v40, 0xbfb8aa3b, v36
	v_mul_f32_e32 v41, 0xbfb8aa3b, v37
	v_exp_f32_e32 v40, v40
	v_exp_f32_e32 v41, v41
	v_add_f32_e32 v40, 1.0, v40
	v_add_f32_e32 v41, 1.0, v41
	v_rcp_f32_e32 v40, v40
	v_rcp_f32_e32 v41, v41
	s_nop 0
	v_pk_mul_f32 v[48:49], v[36:37], v[40:41]
	v_lshlrev_b32_e32 v36, 16, v38
	v_and_b32_e32 v37, 0xffff0000, v38
	v_lshlrev_b32_e32 v40, 16, v42
	v_and_b32_e32 v41, 0xffff0000, v42
	v_pk_fma_f32 v[36:37], v[52:53], v[36:37], 0 op_sel_hi:[1,1,0]
	v_lshlrev_b32_e32 v42, 16, v51
	v_pk_fma_f32 v[36:37], v[82:83], v[40:41], v[36:37]
	v_pk_mul_f32 v[72:73], v[48:49], v[48:49]
	v_pk_fma_f32 v[36:37], v[90:91], v[44:45], v[36:37]
	s_waitcnt vmcnt(0)
; __device__ __forceinline__ float sigmoidf_(float x) { return __builtin_amdgcn_rcpf(1.f + __expf(-x)); }
; __device__ __forceinline__ float delta_prep(const Params& p, int l, int h, bool isP, int grow0, int t0, int nvalid, int bb, char* sm) {
;     ...
; #pragma unroll
;       for (int j = 0; j < 4; ++j) {
;         float f[16], wv[16];
;         const bfraw* s = raw + (arr * 67 + rl + j) * 136 + cg8 * 16;
;         unpack8(*(const uint4*)s, f); unpack8(*(const uint4*)(s + 8), f + 8);
; #pragma unroll
;         for (int e = 0; e < 4; ++e) {
;           float4 t4 = *(const float4*)(cw + j * 1536 + arr * 512 + e * 4);
;           wv[e * 4] = t4.x; wv[e * 4 + 1] = t4.y; wv[e * 4 + 2] = t4.z; wv[e * 4 + 3] = t4.w;
;         }
; #pragma unroll
;         for (int e = 0; e < 16; ++e) y[e] += f[e] * wv[e];
;       }
;       float ss = 0.f;
; #pragma unroll
;       for (int e = 0; e < 16; ++e) { float v = y[e]; v = v * sigmoidf_(v); y[e] = v; ss += v * v; }
;       if (arr < 2) {
;         ss += __shfl_xor(ss, 1); ss += __shfl_xor(ss, 2); ss += __shfl_xor(ss, 4);
;         float sc = rsqrtf(ss + EPS) * (arr == 0 ? 0.08838834764831845f : 1.f);
; #pragma unroll
;         for (int e = 0; e < 16; ++e) y[e] *= sc;
;       }
	v_pk_fma_f32 v[36:37], v[98:99], v[74:75], v[36:37]
	s_nop 0
	v_mul_f32_e32 v38, 0xbfb8aa3b, v36
	v_exp_f32_e32 v38, v38
	s_nop 0
	v_add_f32_e32 v38, 1.0, v38
	v_rcp_f32_e32 v40, v38
	v_mul_f32_e32 v38, 0xbfb8aa3b, v37
	v_exp_f32_e32 v38, v38
	s_nop 0
	v_add_f32_e32 v38, 1.0, v38
	v_rcp_f32_e32 v41, v38
	v_lshlrev_b32_e32 v38, 16, v43
	v_pk_mul_f32 v[52:53], v[36:37], v[40:41]
	v_lshlrev_b32_e32 v36, 16, v39
	v_and_b32_e32 v37, 0xffff0000, v39
	v_and_b32_e32 v39, 0xffff0000, v43
	v_pk_fma_f32 v[36:37], v[54:55], v[36:37], 0 op_sel_hi:[1,1,0]
	v_lshlrev_b32_e32 v40, 16, v47
	v_and_b32_e32 v41, 0xffff0000, v47
	v_pk_fma_f32 v[36:37], v[84:85], v[38:39], v[36:37]
	v_and_b32_e32 v43, 0xffff0000, v51
	v_pk_fma_f32 v[36:37], v[92:93], v[40:41], v[36:37]
	ds_read_b128 v[44:47], v76 offset:832
	v_pk_fma_f32 v[36:37], v[100:101], v[42:43], v[36:37]
	ds_read_b128 v[40:43], v76 offset:560
	v_mul_f32_e32 v38, 0xbfb8aa3b, v36
	v_mul_f32_e32 v39, 0xbfb8aa3b, v37
	v_exp_f32_e32 v38, v38
	v_exp_f32_e32 v39, v39
	s_waitcnt lgkmcnt(0)
	v_lshlrev_b32_e32 v82, 16, v40
	v_and_b32_e32 v83, 0xffff0000, v40
	v_add_f32_e32 v38, 1.0, v38
	v_add_f32_e32 v39, 1.0, v39
	v_rcp_f32_e32 v38, v38
	v_rcp_f32_e32 v39, v39
	v_and_b32_e32 v77, 0xffff0000, v44
	v_pk_mul_f32 v[74:75], v[52:53], v[52:53]
	v_pk_mul_f32 v[50:51], v[36:37], v[38:39]
	ds_read_b128 v[36:39], v76 offset:288
	v_lshlrev_b32_e32 v76, 16, v44
	v_pk_mul_f32 v[54:55], v[50:51], v[50:51]
	s_waitcnt lgkmcnt(0)
	v_lshlrev_b32_e32 v80, 16, v36
	v_and_b32_e32 v81, 0xffff0000, v36
	v_pk_fma_f32 v[12:13], v[24:25], v[80:81], v[12:13]
	v_lshlrev_b32_e32 v36, 16, v45
	v_pk_fma_f32 v[12:13], v[28:29], v[82:83], v[12:13]
	v_lshlrev_b32_e32 v28, 16, v37
	v_pk_fma_f32 v[12:13], v[32:33], v[76:77], v[12:13]
	v_and_b32_e32 v29, 0xffff0000, v37
	v_mul_f32_e32 v0, 0xbfb8aa3b, v12
	v_exp_f32_e32 v0, v0
	v_lshlrev_b32_e32 v32, 16, v41
	v_and_b32_e32 v33, 0xffff0000, v41
	v_and_b32_e32 v37, 0xffff0000, v45
	v_add_f32_e32 v0, 1.0, v0
	v_rcp_f32_e32 v24, v0
	v_mul_f32_e32 v0, 0xbfb8aa3b, v13
	v_exp_f32_e32 v0, v0
	s_nop 0
	v_add_f32_e32 v0, 1.0, v0
	v_rcp_f32_e32 v25, v0
	v_lshlrev_b32_e32 v0, 16, v1
	v_and_b32_e32 v1, 0xffff0000, v1
	v_pk_fma_f32 v[0:1], v[14:15], v[0:1], 0 op_sel_hi:[1,1,0]
	v_pk_mul_f32 v[12:13], v[12:13], v[24:25]
	v_pk_fma_f32 v[0:1], v[26:27], v[28:29], v[0:1]
	v_lshlrev_b32_e32 v26, 16, v2
	v_and_b32_e32 v27, 0xffff0000, v2
	v_lshlrev_b32_e32 v28, 16, v38
	v_and_b32_e32 v29, 0xffff0000, v38
	v_pk_fma_f32 v[4:5], v[4:5], v[26:27], 0 op_sel_hi:[1,1,0]
	v_pk_fma_f32 v[0:1], v[30:31], v[32:33], v[0:1]
	v_lshlrev_b32_e32 v30, 16, v42
	v_and_b32_e32 v31, 0xffff0000, v42
	v_pk_fma_f32 v[4:5], v[8:9], v[28:29], v[4:5]
	v_lshlrev_b32_e32 v32, 16, v46
	v_and_b32_e32 v33, 0xffff0000, v46
	v_pk_fma_f32 v[4:5], v[16:17], v[30:31], v[4:5]
	v_pk_fma_f32 v[0:1], v[34:35], v[36:37], v[0:1]
	v_pk_fma_f32 v[4:5], v[20:21], v[32:33], v[4:5]
	v_mul_f32_e32 v14, 0xbfb8aa3b, v0
	v_mul_f32_e32 v2, 0xbfb8aa3b, v4
	v_exp_f32_e32 v2, v2
	v_mul_f32_e32 v15, 0xbfb8aa3b, v1
	v_lshlrev_b32_e32 v16, 16, v39
	v_and_b32_e32 v17, 0xffff0000, v39
	v_add_f32_e32 v2, 1.0, v2
	v_rcp_f32_e32 v8, v2
	v_mul_f32_e32 v2, 0xbfb8aa3b, v5
	v_exp_f32_e32 v2, v2
	v_exp_f32_e32 v14, v14
	v_exp_f32_e32 v15, v15
	v_lshlrev_b32_e32 v20, 16, v43
	v_add_f32_e32 v2, 1.0, v2
	v_rcp_f32_e32 v9, v2
	v_lshlrev_b32_e32 v2, 16, v3
	v_and_b32_e32 v3, 0xffff0000, v3
	v_pk_fma_f32 v[2:3], v[6:7], v[2:3], 0 op_sel_hi:[1,1,0]
	v_and_b32_e32 v21, 0xffff0000, v43
	v_pk_fma_f32 v[2:3], v[10:11], v[16:17], v[2:3]
	v_lshlrev_b32_e32 v26, 16, v47
	v_and_b32_e32 v27, 0xffff0000, v47
	v_pk_fma_f32 v[2:3], v[18:19], v[20:21], v[2:3]
	v_add_f32_e32 v10, v70, v71
	v_pk_fma_f32 v[2:3], v[22:23], v[26:27], v[2:3]
	v_add_f32_e32 v10, v10, v72
	v_mul_f32_e32 v6, 0xbfb8aa3b, v2
	v_mul_f32_e32 v7, 0xbfb8aa3b, v3
	v_add_f32_e32 v14, 1.0, v14
	v_add_f32_e32 v15, 1.0, v15
	v_exp_f32_e32 v6, v6
	v_exp_f32_e32 v7, v7
	v_add_f32_e32 v10, v10, v73
	v_rcp_f32_e32 v14, v14
	v_rcp_f32_e32 v15, v15
	v_add_f32_e32 v10, v10, v74
	v_add_f32_e32 v10, v10, v75
	v_add_f32_e32 v10, v10, v54
	v_pk_mul_f32 v[24:25], v[12:13], v[12:13]
	v_add_f32_e32 v6, 1.0, v6
	v_add_f32_e32 v7, 1.0, v7
	v_add_f32_e32 v10, v10, v55
	v_pk_mul_f32 v[0:1], v[0:1], v[14:15]
	v_rcp_f32_e32 v6, v6
	v_rcp_f32_e32 v7, v7
	v_add_f32_e32 v10, v10, v24
	v_pk_mul_f32 v[14:15], v[0:1], v[0:1]
	v_add_f32_e32 v10, v10, v25
	v_pk_mul_f32 v[4:5], v[4:5], v[8:9]
	v_add_f32_e32 v10, v10, v14
	v_pk_mul_f32 v[8:9], v[4:5], v[4:5]
	v_add_f32_e32 v10, v10, v15
	v_pk_mul_f32 v[2:3], v[2:3], v[6:7]
	v_add_f32_e32 v8, v10, v8
	v_pk_mul_f32 v[6:7], v[2:3], v[2:3]
	v_add_f32_e32 v8, v8, v9
	v_add_f32_e32 v6, v8, v6
	v_and_b32_e32 v8, 64, v158
	v_add_f32_e32 v6, v6, v7
	v_xor_b32_e32 v7, 1, v158
	v_add_u32_e32 v8, 64, v8
	v_cmp_lt_i32_e64 s[0:1], v7, v8
	s_nop 1
	v_cndmask_b32_e64 v7, v158, v7, s[0:1]
	v_lshlrev_b32_e32 v7, 2, v7
	ds_bpermute_b32 v7, v7, v6
	s_waitcnt lgkmcnt(0)
	v_add_f32_e32 v6, v6, v7
	v_xor_b32_e32 v7, 2, v158
	v_cmp_lt_i32_e64 s[0:1], v7, v8
	s_nop 1
	v_cndmask_b32_e64 v7, v158, v7, s[0:1]
	v_lshlrev_b32_e32 v7, 2, v7
	ds_bpermute_b32 v7, v7, v6
	s_waitcnt lgkmcnt(0)
	v_add_f32_e32 v6, v6, v7
	v_xor_b32_e32 v7, 4, v158
	v_cmp_lt_i32_e64 s[0:1], v7, v8
	s_nop 1
	v_cndmask_b32_e64 v7, v158, v7, s[0:1]
	v_lshlrev_b32_e32 v7, 2, v7
	ds_bpermute_b32 v7, v7, v6
	s_waitcnt lgkmcnt(0)
	v_add_f32_e32 v6, v6, v7
	v_add_f32_e32 v6, 0x358637bd, v6
	v_cmp_gt_f32_e64 s[0:1], s77, v6
	v_mul_f32_e32 v7, 0x4b800000, v6
	s_nop 0
	v_cndmask_b32_e64 v6, v6, v7, s[0:1]
	v_rsq_f32_e32 v6, v6
	s_nop 0
	v_mul_f32_e32 v7, 0x45800000, v6
	v_cndmask_b32_e64 v6, v6, v7, s[0:1]
	v_mul_f32_e32 v6, 0x3db504f3, v6
	v_pk_mul_f32 v[82:83], v[68:69], v[6:7] op_sel_hi:[1,0]
	v_pk_mul_f32 v[78:79], v[48:49], v[6:7] op_sel_hi:[1,0]
	v_pk_mul_f32 v[74:75], v[52:53], v[6:7] op_sel_hi:[1,0]
	v_pk_mul_f32 v[70:71], v[50:51], v[6:7] op_sel_hi:[1,0]
	v_pk_mul_f32 v[80:81], v[12:13], v[6:7] op_sel_hi:[1,0]
	v_pk_mul_f32 v[76:77], v[0:1], v[6:7] op_sel_hi:[1,0]
	v_pk_mul_f32 v[72:73], v[4:5], v[6:7] op_sel_hi:[1,0]
	v_pk_mul_f32 v[68:69], v[2:3], v[6:7] op_sel_hi:[1,0]

; __device__ __forceinline__ float sigmoidf_(float x) { return __builtin_amdgcn_rcpf(1.f + __expf(-x)); }
; __device__ __forceinline__ float delta_prep(const Params& p, int l, int h, bool isP, int grow0, int t0, int nvalid, int bb, char* sm) {
;     ...
;   __syncthreads();
;   const int rl = tid >> 3, cg8 = tid & 7;
;   float qf[16], kf[16], vf[16];
;   {
;     const float* cw = p.conv_w + (size_t)l * 4 * 1536 + h * 128 + cg8 * 16;
; #pragma unroll
;     for (int arr = 0; arr < 3; ++arr) {
;       float y[16];
; #pragma unroll
;       for (int j = 0; j < 16; ++j) y[j] = 0.f;
;       if (rl < nvalid) {
; #pragma unroll
;       for (int j = 0; j < 4; ++j) {
;         float f[16], wv[16];
;         const bfraw* s = raw + (arr * 67 + rl + j) * 136 + cg8 * 16;
;         unpack8(*(const uint4*)s, f); unpack8(*(const uint4*)(s + 8), f + 8);
; #pragma unroll
;         for (int e = 0; e < 4; ++e) {
;           float4 t4 = *(const float4*)(cw + j * 1536 + arr * 512 + e * 4);
;           wv[e * 4] = t4.x; wv[e * 4 + 1] = t4.y; wv[e * 4 + 2] = t4.z; wv[e * 4 + 3] = t4.w;
;         }
; #pragma unroll
;         for (int e = 0; e < 16; ++e) y[e] += f[e] * wv[e];
;       }
;       float ss = 0.f;
; #pragma unroll
;       for (int e = 0; e < 16; ++e) { float v = y[e]; v = v * sigmoidf_(v); y[e] = v; ss += v * v; }
.LBB0_4102:
	s_or_b64 exec, exec, s[4:5]
	s_lshl_b32 s0, s29, 2
	v_readlane_b32 s1, v247, 63
	v_lshlrev_b32_e32 v166, 4, v0
	s_add_u32 s0, s1, s0
	v_readlane_b32 s1, v246, 0
	v_and_b32_e32 v65, 0x70, v166
	v_ashrrev_i32_e32 v3, 3, v0
	s_addc_u32 s1, s1, 0
	v_lshlrev_b32_e32 v98, 2, v65
	v_mov_b32_e32 v99, v2
	v_lshl_add_u64 v[60:61], s[0:1], 0, v[98:99]
	s_mov_b64 s[98:99], 0x800
	global_load_dword v180, v[60:61], off
	v_lshl_add_u64 v[182:183], v[60:61], 0, s[98:99]
	global_load_dword v180, v[182:183], off
	v_lshl_add_u64 v[182:183], v[182:183], 0, s[98:99]
	global_load_dword v180, v[182:183], off
	v_lshl_add_u64 v[182:183], v[182:183], 0, s[98:99]
	global_load_dword v180, v[182:183], off
	v_lshl_add_u64 v[182:183], v[182:183], 0, s[98:99]
	global_load_dword v180, v[182:183], off
	v_lshl_add_u64 v[182:183], v[182:183], 0, s[98:99]
	global_load_dword v180, v[182:183], off
	v_lshl_add_u64 v[182:183], v[182:183], 0, s[98:99]
	global_load_dword v180, v[182:183], off
	v_lshl_add_u64 v[182:183], v[182:183], 0, s[98:99]
	global_load_dword v180, v[182:183], off
	v_lshl_add_u64 v[182:183], v[182:183], 0, s[98:99]
	global_load_dword v180, v[182:183], off
	v_lshl_add_u64 v[182:183], v[182:183], 0, s[98:99]
	global_load_dword v180, v[182:183], off
	v_lshl_add_u64 v[182:183], v[182:183], 0, s[98:99]
	global_load_dword v180, v[182:183], off
	v_lshl_add_u64 v[182:183], v[182:183], 0, s[98:99]
	global_load_dword v180, v[182:183], off
	v_cmp_gt_i32_e32 vcc, 8, v3
	v_lshl_add_u32 v62, v65, 1, s48
	v_mov_b32_e32 v66, 0
	v_mov_b32_e32 v70, 0
	v_mov_b32_e32 v71, 0
	v_mov_b32_e32 v74, 0
	v_mov_b32_e32 v75, 0
	v_mov_b32_e32 v78, 0
	v_mov_b32_e32 v79, 0
	v_mov_b32_e32 v82, 0
	v_mov_b32_e32 v83, 0
	v_mov_b32_e32 v68, 0
	v_mov_b32_e32 v69, 0
	v_mov_b32_e32 v72, 0
	v_mov_b32_e32 v73, 0
	v_mov_b32_e32 v76, 0
	v_mov_b32_e32 v77, 0
	v_mov_b32_e32 v80, 0
	v_mov_b32_e32 v81, 0
	s_waitcnt lgkmcnt(0)
	s_barrier
	s_and_saveexec_b64 s[2:3], vcc
	s_cbranch_execz .LBB0_4104
	v_mad_u64_u32 v[76:77], s[0:1], v3, s50, v[62:63]
	ds_read_b128 v[40:43], v76
	s_waitcnt vmcnt(0)
	ds_read_b128 v[4:7], v76 offset:16
	ds_read_b128 v[44:47], v76 offset:272
	ds_read_b128 v[48:51], v76 offset:544
	ds_read_b128 v[52:55], v76 offset:816
	global_load_dwordx4 v[8:11], v[60:61], off offset:48
	global_load_dwordx4 v[16:19], v[60:61], off offset:32
	global_load_dwordx4 v[56:59], v[60:61], off offset:16
	global_load_dwordx4 v[70:73], v[60:61], off
	s_mov_b64 s[0:1], 0x1800
	v_lshl_add_u64 v[20:21], v[60:61], 0, s[0:1]
	s_mov_b64 s[0:1], 0x3000
	v_lshl_add_u64 v[24:25], v[60:61], 0, s[0:1]
	s_mov_b64 s[0:1], 0x4800
	s_waitcnt lgkmcnt(4)
	v_lshlrev_b32_e32 v12, 16, v40
	v_lshl_add_u64 v[68:69], v[60:61], 0, s[0:1]
	v_and_b32_e32 v13, 0xffff0000, v40
	s_movk_i32 s0, 0x1000
	s_waitcnt lgkmcnt(2)
	v_lshlrev_b32_e32 v22, 16, v44
	v_and_b32_e32 v23, 0xffff0000, v44
	s_waitcnt lgkmcnt(1)
	v_lshlrev_b32_e32 v26, 16, v48
	v_and_b32_e32 v27, 0xffff0000, v48
	s_waitcnt lgkmcnt(0)
	v_lshlrev_b32_e32 v74, 16, v52
	v_and_b32_e32 v75, 0xffff0000, v52
	v_lshlrev_b32_e32 v44, 16, v45
	v_and_b32_e32 v45, 0xffff0000, v45
	v_lshlrev_b32_e32 v48, 16, v49
	v_and_b32_e32 v49, 0xffff0000, v49
	v_lshlrev_b32_e32 v52, 16, v53
	v_and_b32_e32 v53, 0xffff0000, v53
	s_waitcnt vmcnt(0)
	v_pk_fma_f32 v[32:33], v[70:71], v[12:13], 0 op_sel_hi:[1,1,0]
	v_add_co_u32_e64 v12, s[0:1], s0, v60
	s_nop 1
	v_addc_co_u32_e64 v13, s[0:1], 0, v61, s[0:1]
	global_load_dwordx4 v[78:81], v[12:13], off offset:2048
	s_nop 0
	global_load_dwordx4 v[12:15], v[20:21], off offset:48
	global_load_dwordx4 v[28:31], v[20:21], off offset:32
	global_load_dwordx4 v[82:85], v[20:21], off offset:16
	s_movk_i32 s0, 0x3000
	v_add_co_u32_e64 v20, s[0:1], s0, v60
	s_waitcnt vmcnt(3)
	v_pk_fma_f32 v[36:37], v[78:79], v[22:23], v[32:33]
	v_addc_co_u32_e64 v21, s[0:1], 0, v61, s[0:1]
	global_load_dwordx4 v[86:89], v[20:21], off
	s_nop 0
	global_load_dwordx4 v[20:23], v[24:25], off offset:48
	global_load_dwordx4 v[32:35], v[24:25], off offset:32
	global_load_dwordx4 v[90:93], v[24:25], off offset:16
	s_movk_i32 s0, 0x4000
	v_add_co_u32_e64 v24, s[0:1], s0, v60
	v_lshlrev_b32_e32 v78, 16, v4
	s_nop 0
	v_addc_co_u32_e64 v25, s[0:1], 0, v61, s[0:1]
	v_and_b32_e32 v79, 0xffff0000, v4
	v_pk_fma_f32 v[16:17], v[16:17], v[78:79], 0 op_sel_hi:[1,1,0]
	s_waitcnt vmcnt(3)
	v_pk_fma_f32 v[70:71], v[86:87], v[26:27], v[36:37]
	global_load_dwordx4 v[94:97], v[24:25], off offset:2048
	s_nop 0
	global_load_dwordx4 v[24:27], v[68:69], off offset:48
	global_load_dwordx4 v[36:39], v[68:69], off offset:32
	global_load_dwordx4 v[100:103], v[68:69], off offset:16
	s_waitcnt vmcnt(3)
	v_pk_fma_f32 v[68:69], v[94:95], v[74:75], v[70:71]
	s_nop 0
	v_mul_f32_e32 v40, 0xbfb8aa3b, v68
	v_exp_f32_e32 v40, v40
	v_lshlrev_b32_e32 v74, 16, v54
	v_and_b32_e32 v75, 0xffff0000, v54
	v_add_f32_e32 v40, 1.0, v40
	v_rcp_f32_e32 v70, v40
	v_mul_f32_e32 v40, 0xbfb8aa3b, v69
	v_exp_f32_e32 v40, v40
	s_nop 0
	v_add_f32_e32 v40, 1.0, v40
	v_rcp_f32_e32 v71, v40
	v_lshlrev_b32_e32 v40, 16, v41
	v_and_b32_e32 v41, 0xffff0000, v41
	v_pk_fma_f32 v[40:41], v[72:73], v[40:41], 0 op_sel_hi:[1,1,0]
	v_pk_mul_f32 v[68:69], v[68:69], v[70:71]
	v_pk_fma_f32 v[40:41], v[80:81], v[44:45], v[40:41]
	v_pk_mul_f32 v[70:71], v[68:69], v[68:69]
	v_pk_fma_f32 v[40:41], v[88:89], v[48:49], v[40:41]
	v_lshlrev_b32_e32 v48, 16, v50
	v_pk_fma_f32 v[40:41], v[96:97], v[52:53], v[40:41]
	v_and_b32_e32 v49, 0xffff0000, v50
	v_mul_f32_e32 v44, 0xbfb8aa3b, v40
	v_mul_f32_e32 v45, 0xbfb8aa3b, v41
	v_exp_f32_e32 v44, v44
	v_exp_f32_e32 v45, v45
	v_add_f32_e32 v44, 1.0, v44
	v_add_f32_e32 v45, 1.0, v45
	v_rcp_f32_e32 v44, v44
	v_rcp_f32_e32 v45, v45
	s_nop 0
	v_pk_mul_f32 v[52:53], v[40:41], v[44:45]
	v_lshlrev_b32_e32 v40, 16, v42
	v_and_b32_e32 v41, 0xffff0000, v42
	v_lshlrev_b32_e32 v44, 16, v46
	v_and_b32_e32 v45, 0xffff0000, v46
	v_pk_fma_f32 v[40:41], v[56:57], v[40:41], 0 op_sel_hi:[1,1,0]
	v_lshlrev_b32_e32 v46, 16, v55
	v_pk_fma_f32 v[40:41], v[82:83], v[44:45], v[40:41]
	v_pk_mul_f32 v[72:73], v[52:53], v[52:53]
	v_pk_fma_f32 v[40:41], v[90:91], v[48:49], v[40:41]
	s_waitcnt vmcnt(0)
; __device__ __forceinline__ float sigmoidf_(float x) { return __builtin_amdgcn_rcpf(1.f + __expf(-x)); }
; __device__ __forceinline__ float delta_prep(const Params& p, int l, int h, bool isP, int grow0, int t0, int nvalid, int bb, char* sm) {
;     ...
; #pragma unroll
;       for (int j = 0; j < 4; ++j) {
;         float f[16], wv[16];
;         const bfraw* s = raw + (arr * 67 + rl + j) * 136 + cg8 * 16;
;         unpack8(*(const uint4*)s, f); unpack8(*(const uint4*)(s + 8), f + 8);
; #pragma unroll
;         for (int e = 0; e < 4; ++e) {
;           float4 t4 = *(const float4*)(cw + j * 1536 + arr * 512 + e * 4);
;           wv[e * 4] = t4.x; wv[e * 4 + 1] = t4.y; wv[e * 4 + 2] = t4.z; wv[e * 4 + 3] = t4.w;
;         }
; #pragma unroll
;         for (int e = 0; e < 16; ++e) y[e] += f[e] * wv[e];
;       }
;       float ss = 0.f;
; #pragma unroll
;       for (int e = 0; e < 16; ++e) { float v = y[e]; v = v * sigmoidf_(v); y[e] = v; ss += v * v; }
;       if (arr < 2) {
;         ss += __shfl_xor(ss, 1); ss += __shfl_xor(ss, 2); ss += __shfl_xor(ss, 4);
;         float sc = rsqrtf(ss + EPS) * (arr == 0 ? 0.08838834764831845f : 1.f);
; #pragma unroll
;         for (int e = 0; e < 16; ++e) y[e] *= sc;
;       }
	v_pk_fma_f32 v[40:41], v[100:101], v[74:75], v[40:41]
	s_nop 0
	v_mul_f32_e32 v42, 0xbfb8aa3b, v40
	v_exp_f32_e32 v42, v42
	s_nop 0
	v_add_f32_e32 v42, 1.0, v42
	v_rcp_f32_e32 v44, v42
	v_mul_f32_e32 v42, 0xbfb8aa3b, v41
	v_exp_f32_e32 v42, v42
	s_nop 0
	v_add_f32_e32 v42, 1.0, v42
	v_rcp_f32_e32 v45, v42
	v_lshlrev_b32_e32 v42, 16, v47
	v_pk_mul_f32 v[56:57], v[40:41], v[44:45]
	v_lshlrev_b32_e32 v40, 16, v43
	v_and_b32_e32 v41, 0xffff0000, v43
	v_and_b32_e32 v43, 0xffff0000, v47
	v_pk_fma_f32 v[40:41], v[58:59], v[40:41], 0 op_sel_hi:[1,1,0]
	v_lshlrev_b32_e32 v44, 16, v51
	v_and_b32_e32 v45, 0xffff0000, v51
	v_pk_fma_f32 v[40:41], v[84:85], v[42:43], v[40:41]
	v_and_b32_e32 v47, 0xffff0000, v55
	v_pk_fma_f32 v[40:41], v[92:93], v[44:45], v[40:41]
	ds_read_b128 v[48:51], v76 offset:832
	v_pk_fma_f32 v[40:41], v[102:103], v[46:47], v[40:41]
	ds_read_b128 v[44:47], v76 offset:560
	v_mul_f32_e32 v42, 0xbfb8aa3b, v40
	v_mul_f32_e32 v43, 0xbfb8aa3b, v41
	v_exp_f32_e32 v42, v42
	v_exp_f32_e32 v43, v43
	s_waitcnt lgkmcnt(0)
	v_lshlrev_b32_e32 v82, 16, v44
	v_and_b32_e32 v83, 0xffff0000, v44
	v_add_f32_e32 v42, 1.0, v42
	v_add_f32_e32 v43, 1.0, v43
	v_rcp_f32_e32 v42, v42
	v_rcp_f32_e32 v43, v43
	v_and_b32_e32 v77, 0xffff0000, v48
	v_pk_mul_f32 v[74:75], v[56:57], v[56:57]
	v_pk_mul_f32 v[54:55], v[40:41], v[42:43]
	ds_read_b128 v[40:43], v76 offset:288
	v_lshlrev_b32_e32 v76, 16, v48
	v_pk_mul_f32 v[58:59], v[54:55], v[54:55]
	s_waitcnt lgkmcnt(0)
	v_lshlrev_b32_e32 v80, 16, v40
	v_and_b32_e32 v81, 0xffff0000, v40
	v_pk_fma_f32 v[16:17], v[28:29], v[80:81], v[16:17]
	v_lshlrev_b32_e32 v40, 16, v49
	v_pk_fma_f32 v[16:17], v[32:33], v[82:83], v[16:17]
	v_lshlrev_b32_e32 v32, 16, v41
	v_pk_fma_f32 v[16:17], v[36:37], v[76:77], v[16:17]
	v_and_b32_e32 v33, 0xffff0000, v41
	v_mul_f32_e32 v4, 0xbfb8aa3b, v16
	v_exp_f32_e32 v4, v4
	v_lshlrev_b32_e32 v36, 16, v45
	v_and_b32_e32 v37, 0xffff0000, v45
	v_and_b32_e32 v41, 0xffff0000, v49
	v_add_f32_e32 v4, 1.0, v4
	v_rcp_f32_e32 v28, v4
	v_mul_f32_e32 v4, 0xbfb8aa3b, v17
	v_exp_f32_e32 v4, v4
	s_nop 0
	v_add_f32_e32 v4, 1.0, v4
	v_rcp_f32_e32 v29, v4
	v_lshlrev_b32_e32 v4, 16, v5
	v_and_b32_e32 v5, 0xffff0000, v5
	v_pk_fma_f32 v[4:5], v[18:19], v[4:5], 0 op_sel_hi:[1,1,0]
	v_pk_mul_f32 v[16:17], v[16:17], v[28:29]
	v_pk_fma_f32 v[4:5], v[30:31], v[32:33], v[4:5]
	v_lshlrev_b32_e32 v30, 16, v6
	v_and_b32_e32 v31, 0xffff0000, v6
	v_lshlrev_b32_e32 v32, 16, v42
	v_and_b32_e32 v33, 0xffff0000, v42
	v_pk_fma_f32 v[8:9], v[8:9], v[30:31], 0 op_sel_hi:[1,1,0]
	v_pk_fma_f32 v[4:5], v[34:35], v[36:37], v[4:5]
	v_lshlrev_b32_e32 v34, 16, v46
	v_and_b32_e32 v35, 0xffff0000, v46
	v_pk_fma_f32 v[8:9], v[12:13], v[32:33], v[8:9]
	v_lshlrev_b32_e32 v36, 16, v50
	v_and_b32_e32 v37, 0xffff0000, v50
	v_pk_fma_f32 v[8:9], v[20:21], v[34:35], v[8:9]
	v_pk_fma_f32 v[4:5], v[38:39], v[40:41], v[4:5]
	v_pk_fma_f32 v[8:9], v[24:25], v[36:37], v[8:9]
	v_mul_f32_e32 v18, 0xbfb8aa3b, v4
	v_mul_f32_e32 v6, 0xbfb8aa3b, v8
	v_exp_f32_e32 v6, v6
	v_mul_f32_e32 v19, 0xbfb8aa3b, v5
	v_lshlrev_b32_e32 v20, 16, v43
	v_and_b32_e32 v21, 0xffff0000, v43
	v_add_f32_e32 v6, 1.0, v6
	v_rcp_f32_e32 v12, v6
	v_mul_f32_e32 v6, 0xbfb8aa3b, v9
	v_exp_f32_e32 v6, v6
	v_exp_f32_e32 v18, v18
	v_exp_f32_e32 v19, v19
	v_lshlrev_b32_e32 v24, 16, v47
	v_add_f32_e32 v6, 1.0, v6
	v_rcp_f32_e32 v13, v6
	v_lshlrev_b32_e32 v6, 16, v7
	v_and_b32_e32 v7, 0xffff0000, v7
	v_pk_fma_f32 v[6:7], v[10:11], v[6:7], 0 op_sel_hi:[1,1,0]
	v_and_b32_e32 v25, 0xffff0000, v47
	v_pk_fma_f32 v[6:7], v[14:15], v[20:21], v[6:7]
	v_lshlrev_b32_e32 v30, 16, v51
	v_and_b32_e32 v31, 0xffff0000, v51
	v_pk_fma_f32 v[6:7], v[22:23], v[24:25], v[6:7]
	v_add_f32_e32 v14, v70, v71
	v_pk_fma_f32 v[6:7], v[26:27], v[30:31], v[6:7]
	v_add_f32_e32 v14, v14, v72
	v_mul_f32_e32 v10, 0xbfb8aa3b, v6
	v_mul_f32_e32 v11, 0xbfb8aa3b, v7
	v_add_f32_e32 v18, 1.0, v18
	v_add_f32_e32 v19, 1.0, v19
	v_exp_f32_e32 v10, v10
	v_exp_f32_e32 v11, v11
	v_add_f32_e32 v14, v14, v73
	v_rcp_f32_e32 v18, v18
	v_rcp_f32_e32 v19, v19
	v_add_f32_e32 v14, v14, v74
	v_add_f32_e32 v14, v14, v75
	v_add_f32_e32 v14, v14, v58
	v_pk_mul_f32 v[28:29], v[16:17], v[16:17]
	v_add_f32_e32 v10, 1.0, v10
	v_add_f32_e32 v11, 1.0, v11
	v_add_f32_e32 v14, v14, v59
	v_pk_mul_f32 v[4:5], v[4:5], v[18:19]
	v_rcp_f32_e32 v10, v10
	v_rcp_f32_e32 v11, v11
	v_add_f32_e32 v14, v14, v28
	v_pk_mul_f32 v[18:19], v[4:5], v[4:5]
	v_add_f32_e32 v14, v14, v29
	v_pk_mul_f32 v[8:9], v[8:9], v[12:13]
	v_add_f32_e32 v14, v14, v18
	v_pk_mul_f32 v[12:13], v[8:9], v[8:9]
	v_add_f32_e32 v14, v14, v19
	v_pk_mul_f32 v[6:7], v[6:7], v[10:11]
	v_add_f32_e32 v12, v14, v12
	v_pk_mul_f32 v[10:11], v[6:7], v[6:7]
	v_add_f32_e32 v12, v12, v13
	v_add_f32_e32 v10, v12, v10
	v_and_b32_e32 v12, 64, v160
	v_add_f32_e32 v10, v10, v11
	v_xor_b32_e32 v11, 1, v160
	v_add_u32_e32 v12, 64, v12
	v_cmp_lt_i32_e64 s[0:1], v11, v12
	s_nop 1
	v_cndmask_b32_e64 v11, v160, v11, s[0:1]
	v_lshlrev_b32_e32 v11, 2, v11
	ds_bpermute_b32 v11, v11, v10
	s_waitcnt lgkmcnt(0)
	v_add_f32_e32 v10, v10, v11
	v_xor_b32_e32 v11, 2, v160
	v_cmp_lt_i32_e64 s[0:1], v11, v12
	s_nop 1
	v_cndmask_b32_e64 v11, v160, v11, s[0:1]
	v_lshlrev_b32_e32 v11, 2, v11
	ds_bpermute_b32 v11, v11, v10
	s_waitcnt lgkmcnt(0)
	v_add_f32_e32 v10, v10, v11
	v_xor_b32_e32 v11, 4, v160
	v_cmp_lt_i32_e64 s[0:1], v11, v12
	s_nop 1
	v_cndmask_b32_e64 v11, v160, v11, s[0:1]
	v_lshlrev_b32_e32 v11, 2, v11
	ds_bpermute_b32 v11, v11, v10
	s_mov_b32 s0, 0x800000
	s_waitcnt lgkmcnt(0)
	v_add_f32_e32 v10, v10, v11
	v_add_f32_e32 v10, 0x358637bd, v10
	v_cmp_gt_f32_e64 s[0:1], s0, v10
	v_mul_f32_e32 v11, 0x4b800000, v10
	s_nop 0
	v_cndmask_b32_e64 v10, v10, v11, s[0:1]
	v_rsq_f32_e32 v10, v10
	s_nop 0
	v_mul_f32_e32 v11, 0x45800000, v10
	v_cndmask_b32_e64 v10, v10, v11, s[0:1]
	v_mul_f32_e32 v10, 0x3db504f3, v10
	v_pk_mul_f32 v[82:83], v[68:69], v[10:11] op_sel_hi:[1,0]
	v_pk_mul_f32 v[78:79], v[52:53], v[10:11] op_sel_hi:[1,0]
	v_pk_mul_f32 v[74:75], v[56:57], v[10:11] op_sel_hi:[1,0]
	v_pk_mul_f32 v[70:71], v[54:55], v[10:11] op_sel_hi:[1,0]
	v_pk_mul_f32 v[80:81], v[16:17], v[10:11] op_sel_hi:[1,0]
	v_pk_mul_f32 v[76:77], v[4:5], v[10:11] op_sel_hi:[1,0]
	v_pk_mul_f32 v[72:73], v[8:9], v[10:11] op_sel_hi:[1,0]
	v_pk_mul_f32 v[68:69], v[6:7], v[10:11] op_sel_hi:[1,0]
